# baseline (speedup 1.0000x reference)
; __device__ __forceinline__ unsigned cvt_pk_bf16(float lo, float hi) { unsigned r; asm volatile("v_cvt_pk_bf16_f32 %0, %1, %2" : "=v"(r) : "v"(lo), "v"(hi)); return r; }
; #define LAS __attribute__((address_space(3)))
; __device__ __forceinline__ void attn_phase(LAS unsigned char* lds, bf16_t* Qb, const bf16_t* KVb, const bf16_t* GZ, const float* sinkp) {
;     ...
;         const float inv = 1.f / l_run;
;         int qo = q, ho = h, cro = crr, cho = cch; asm volatile("" : "+v"(qo), "+v"(ho), "+v"(cro), "+v"(cho));
; #pragma unroll
;         for (int dt = 0; dt < 4; ++dt)
; #pragma unroll
;             for (int g4 = 0; g4 < 4; ++g4) {
;                 u32x2 ov; ov.x = cvt_pk_bf16(o[dt][4 * g4] * inv, o[dt][4 * g4 + 1] * inv); ov.y = cvt_pk_bf16(o[dt][4 * g4 + 2] * inv, o[dt][4 * g4 + 3] * inv);
;                 *(LAS u32x2*)(Wl + qo * 256 + (((4 * dt + g4) ^ (qo & 15)) << 4) + 8 * ho) = ov;
;             }
; #pragma unroll 2
;         for (int it = 0; it < 8; ++it) {
;             const int rr = cro + 4 * it, grow = mu ? NREAL + seq * 16 + (rr & 15) : row0 + rr;
;             const u32x4 ovv = *(const LAS u32x4*)(Wl + rr * 256 + ((cho ^ (rr & 15)) << 4));
;             const size_t goff = (size_t)grow * 2048 + head * 128 + cho * 8;
;             const u32x4 gz = *(const u32x4*)(GZ + goff);
.LBB0_183:
	v_div_scale_f32 v64, s[6:7], v173, v173, 1.0
	v_rcp_f32_e32 v65, v64
	v_div_scale_f32 v66, vcc, 1.0, v173, 1.0
	s_movk_i32 s3, 0x50
	v_fma_f32 v67, -v64, v65, 1.0
	v_fmac_f32_e32 v65, v67, v65
	v_mul_f32_e32 v67, v66, v65
	v_fma_f32 v68, -v64, v67, v66
	v_fmac_f32_e32 v67, v68, v65
	v_fma_f32 v64, -v64, v67, v66
	v_div_fmas_f32 v64, v64, v65, v67
	v_div_fixup_f32 v66, v64, v173, 1.0
	v_mov_b32_e32 v67, v149
	v_mov_b32_e32 v64, v159
	v_mov_b32_e32 v68, v148
	v_mov_b32_e32 v65, v158
	v_mul_f32_e32 v48, v48, v66
	v_mul_f32_e32 v49, v49, v66
	v_cvt_pk_bf16_f32 v48, v48, v49
	v_mul_f32_e32 v49, v50, v66
	v_mul_f32_e32 v50, v51, v66
	v_lshlrev_b32_e32 v69, 8, v68
	v_lshlrev_b32_e32 v67, 3, v67
	v_cvt_pk_bf16_f32 v49, v49, v50
	v_lshlrev_b32_e32 v50, 4, v68
	v_add3_u32 v67, s63, v69, v67
	v_and_b32_e32 v50, 0xf0, v50
	v_add_u32_e32 v51, v67, v50
	ds_write_b64 v51, v[48:49]
	v_mul_f32_e32 v48, v52, v66
	v_mul_f32_e32 v49, v53, v66
	v_cvt_pk_bf16_f32 v48, v48, v49
	v_mul_f32_e32 v49, v54, v66
	v_mul_f32_e32 v51, v55, v66
	v_cvt_pk_bf16_f32 v49, v49, v51
	v_xad_u32 v51, v50, 16, v67
	ds_write_b64 v51, v[48:49]
	v_mul_f32_e32 v48, v56, v66
	v_mul_f32_e32 v49, v57, v66
	v_cvt_pk_bf16_f32 v48, v48, v49
	v_mul_f32_e32 v49, v58, v66
	v_mul_f32_e32 v51, v59, v66
	v_cvt_pk_bf16_f32 v49, v49, v51
	v_xad_u32 v51, v50, 32, v67
	ds_write_b64 v51, v[48:49]
	v_mul_f32_e32 v48, v60, v66
	v_mul_f32_e32 v49, v61, v66
	v_cvt_pk_bf16_f32 v48, v48, v49
	v_mul_f32_e32 v49, v62, v66
	v_mul_f32_e32 v51, v63, v66
	v_cvt_pk_bf16_f32 v49, v49, v51
	v_xad_u32 v51, v50, 48, v67
	v_mul_f32_e32 v32, v32, v66
	v_mul_f32_e32 v33, v33, v66
	ds_write_b64 v51, v[48:49]
	v_cvt_pk_bf16_f32 v32, v32, v33
	v_mul_f32_e32 v33, v34, v66
	v_mul_f32_e32 v34, v35, v66
	v_cvt_pk_bf16_f32 v33, v33, v34
	v_xad_u32 v34, v50, 64, v67
	ds_write_b64 v34, v[32:33]
	v_mul_f32_e32 v32, v36, v66
	v_mul_f32_e32 v33, v37, v66
	v_cvt_pk_bf16_f32 v32, v32, v33
	v_mul_f32_e32 v33, v38, v66
	v_mul_f32_e32 v34, v39, v66
	v_cvt_pk_bf16_f32 v33, v33, v34
	v_xad_u32 v34, v50, s3, v67
	ds_write_b64 v34, v[32:33]
	v_mul_f32_e32 v32, v40, v66
	v_mul_f32_e32 v33, v41, v66
	v_cvt_pk_bf16_f32 v32, v32, v33
	v_mul_f32_e32 v33, v42, v66
	v_mul_f32_e32 v34, v43, v66
	v_cvt_pk_bf16_f32 v33, v33, v34
	v_xad_u32 v34, v50, s43, v67
	ds_write_b64 v34, v[32:33]
	v_mul_f32_e32 v32, v44, v66
	v_mul_f32_e32 v33, v45, v66
	v_cvt_pk_bf16_f32 v32, v32, v33
	v_mul_f32_e32 v33, v46, v66
	v_mul_f32_e32 v34, v47, v66
	s_movk_i32 s3, 0x70
	v_cvt_pk_bf16_f32 v33, v33, v34
	v_xad_u32 v34, v50, s3, v67
	v_mul_f32_e32 v16, v16, v66
	v_mul_f32_e32 v17, v17, v66
	ds_write_b64 v34, v[32:33]
	v_cvt_pk_bf16_f32 v16, v16, v17
	v_mul_f32_e32 v17, v18, v66
	v_mul_f32_e32 v18, v19, v66
	s_movk_i32 s3, 0x80
	v_cvt_pk_bf16_f32 v17, v17, v18
	v_xad_u32 v18, v50, s3, v67
	ds_write_b64 v18, v[16:17]
	v_mul_f32_e32 v16, v20, v66
	v_mul_f32_e32 v17, v21, v66
	v_cvt_pk_bf16_f32 v16, v16, v17
	v_mul_f32_e32 v17, v22, v66
	v_mul_f32_e32 v18, v23, v66
	s_movk_i32 s3, 0x90
	v_cvt_pk_bf16_f32 v17, v17, v18
	v_xad_u32 v18, v50, s3, v67
	ds_write_b64 v18, v[16:17]
	v_mul_f32_e32 v16, v24, v66
	v_mul_f32_e32 v17, v25, v66
	v_cvt_pk_bf16_f32 v16, v16, v17
	v_mul_f32_e32 v17, v26, v66
	v_mul_f32_e32 v18, v27, v66
	s_movk_i32 s3, 0xa0
	v_cvt_pk_bf16_f32 v17, v17, v18
	v_xad_u32 v18, v50, s3, v67
	ds_write_b64 v18, v[16:17]
	v_mul_f32_e32 v16, v28, v66
	v_mul_f32_e32 v17, v29, v66
	v_cvt_pk_bf16_f32 v16, v16, v17
	v_mul_f32_e32 v17, v30, v66
	v_mul_f32_e32 v18, v31, v66
	s_movk_i32 s3, 0xb0
	v_cvt_pk_bf16_f32 v17, v17, v18
	v_xad_u32 v18, v50, s3, v67
	v_mul_f32_e32 v0, v0, v66
	v_mul_f32_e32 v1, v1, v66
	ds_write_b64 v18, v[16:17]
	v_cvt_pk_bf16_f32 v0, v0, v1
	v_mul_f32_e32 v1, v2, v66
	v_mul_f32_e32 v2, v3, v66
	s_movk_i32 s3, 0xc0
	v_cvt_pk_bf16_f32 v1, v1, v2
	v_xad_u32 v2, v50, s3, v67
	ds_write_b64 v2, v[0:1]
	v_mul_f32_e32 v0, v4, v66
	v_mul_f32_e32 v1, v5, v66
	v_cvt_pk_bf16_f32 v0, v0, v1
	v_mul_f32_e32 v1, v6, v66
	v_mul_f32_e32 v2, v7, v66
	s_movk_i32 s3, 0xd0
	v_cvt_pk_bf16_f32 v1, v1, v2
	v_xad_u32 v2, v50, s3, v67
	ds_write_b64 v2, v[0:1]
	v_mul_f32_e32 v0, v8, v66
	v_mul_f32_e32 v1, v9, v66
	v_cvt_pk_bf16_f32 v0, v0, v1
	v_mul_f32_e32 v1, v10, v66
	v_mul_f32_e32 v2, v11, v66
	s_movk_i32 s3, 0xe0
	v_cvt_pk_bf16_f32 v1, v1, v2
	v_xad_u32 v2, v50, s3, v67
	ds_write_b64 v2, v[0:1]
	v_mul_f32_e32 v0, v12, v66
	v_mul_f32_e32 v1, v13, v66
	v_cvt_pk_bf16_f32 v0, v0, v1
	v_mul_f32_e32 v1, v14, v66
	v_mul_f32_e32 v2, v15, v66
	s_movk_i32 s3, 0xf0
	v_cvt_pk_bf16_f32 v1, v1, v2
	v_xad_u32 v2, v50, s3, v67
	ds_write_b64 v2, v[0:1]
	v_lshlrev_b32_e32 v0, 3, v64
	v_readlane_b32 s70, v255, 3
	v_ashrrev_i32_e32 v1, 31, v0
	s_add_i32 s61, s61, s64
	v_readlane_b32 s71, v255, 4
	v_lshl_add_u64 v[4:5], v[0:1], 0, s[98:99]
	v_lshl_add_u32 v8, v65, 8, s68
	v_add_u32_e32 v9, s61, v65
	v_add_u32_e32 v8, 0xfffffc00, v8
	v_add_u32_e32 v10, 0, v65
	v_and_b32_e32 v0, 15, v10
	v_or_b32_e32 v0, s60, v0
	v_add_u32_e32 v11, 0, v9
	v_cndmask_b32_e64 v0, v11, v0, s[4:5]
	v_ashrrev_i32_e32 v1, 31, v0
	v_lshlrev_b64 v[0:1], 11, v[0:1]
	v_lshl_add_u64 v[96:97], v[4:5], 0, v[0:1]
	v_lshl_add_u64 v[0:1], v[96:97], 1, s[48:49]
	global_load_dwordx4 v[24:27], v[0:1], off
	v_bitop3_b32 v12, v10, v64, 15 bitop3:0x6c
	v_lshl_add_u32 v12, v12, 4, v8
	ds_read_b128 v[112:115], v12
	v_add_u32_e32 v10, 4, v65
	v_and_b32_e32 v0, 15, v10
	v_or_b32_e32 v0, s60, v0
	v_add_u32_e32 v11, 4, v9
	v_cndmask_b32_e64 v0, v11, v0, s[4:5]
	v_ashrrev_i32_e32 v1, 31, v0
	v_lshlrev_b64 v[0:1], 11, v[0:1]
	v_lshl_add_u64 v[98:99], v[4:5], 0, v[0:1]
	v_lshl_add_u64 v[0:1], v[98:99], 1, s[48:49]
; __device__ __forceinline__ unsigned cvt_pk_bf16(float lo, float hi) { unsigned r; asm volatile("v_cvt_pk_bf16_f32 %0, %1, %2" : "=v"(r) : "v"(lo), "v"(hi)); return r; }
; #define LAS __attribute__((address_space(3)))
; __device__ __forceinline__ void attn_phase(LAS unsigned char* lds, bf16_t* Qb, const bf16_t* KVb, const bf16_t* GZ, const float* sinkp) {
;     ...
;         for (int it = 0; it < 8; ++it) {
;             const int rr = cro + 4 * it, grow = mu ? NREAL + seq * 16 + (rr & 15) : row0 + rr;
;             const u32x4 ovv = *(const LAS u32x4*)(Wl + rr * 256 + ((cho ^ (rr & 15)) << 4));
;             const size_t goff = (size_t)grow * 2048 + head * 128 + cho * 8;
;             const u32x4 gz = *(const u32x4*)(GZ + goff);
;             float fo[8], fg[8]; unpack8(ovv, fo); unpack8(gz, fg);
;             u32x4 res; res.x = cvt_pk_bf16(fo[0] * fg[0], fo[1] * fg[1]); res.y = cvt_pk_bf16(fo[2] * fg[2], fo[3] * fg[3]); res.z = cvt_pk_bf16(fo[4] * fg[4], fo[5] * fg[5]); res.w = cvt_pk_bf16(fo[6] * fg[6], fo[7] * fg[7]);
;             if (!mu || (w < 4 && rr < 16)) *(u32x4*)(Qb + goff) = res;
;         }
	global_load_dwordx4 v[28:31], v[0:1], off
	v_bitop3_b32 v12, v10, v64, 15 bitop3:0x6c
	v_lshl_add_u32 v12, v12, 4, v8
	ds_read_b128 v[116:119], v12 offset:1024
	v_add_u32_e32 v10, 8, v65
	v_and_b32_e32 v0, 15, v10
	v_or_b32_e32 v0, s60, v0
	v_add_u32_e32 v11, 8, v9
	v_cndmask_b32_e64 v0, v11, v0, s[4:5]
	v_ashrrev_i32_e32 v1, 31, v0
	v_lshlrev_b64 v[0:1], 11, v[0:1]
	v_lshl_add_u64 v[100:101], v[4:5], 0, v[0:1]
	v_lshl_add_u64 v[0:1], v[100:101], 1, s[48:49]
	global_load_dwordx4 v[32:35], v[0:1], off
	v_bitop3_b32 v12, v10, v64, 15 bitop3:0x6c
	v_lshl_add_u32 v12, v12, 4, v8
	ds_read_b128 v[120:123], v12 offset:2048
	v_add_u32_e32 v10, 12, v65
	v_and_b32_e32 v0, 15, v10
	v_or_b32_e32 v0, s60, v0
	v_add_u32_e32 v11, 12, v9
	v_cndmask_b32_e64 v0, v11, v0, s[4:5]
	v_ashrrev_i32_e32 v1, 31, v0
	v_lshlrev_b64 v[0:1], 11, v[0:1]
	v_lshl_add_u64 v[102:103], v[4:5], 0, v[0:1]
	v_lshl_add_u64 v[0:1], v[102:103], 1, s[48:49]
	global_load_dwordx4 v[36:39], v[0:1], off
	v_bitop3_b32 v12, v10, v64, 15 bitop3:0x6c
	v_lshl_add_u32 v12, v12, 4, v8
	ds_read_b128 v[124:127], v12 offset:3072
	v_add_u32_e32 v10, 16, v65
	v_and_b32_e32 v0, 15, v10
	v_or_b32_e32 v0, s60, v0
	v_add_u32_e32 v11, 16, v9
	v_cndmask_b32_e64 v0, v11, v0, s[4:5]
	v_ashrrev_i32_e32 v1, 31, v0
	v_lshlrev_b64 v[0:1], 11, v[0:1]
	v_lshl_add_u64 v[104:105], v[4:5], 0, v[0:1]
	v_lshl_add_u64 v[0:1], v[104:105], 1, s[48:49]
	global_load_dwordx4 v[40:43], v[0:1], off
	v_bitop3_b32 v12, v10, v64, 15 bitop3:0x6c
	v_lshl_add_u32 v12, v12, 4, v8
	ds_read_b128 v[128:131], v12 offset:4096
	v_add_u32_e32 v10, 20, v65
	v_and_b32_e32 v0, 15, v10
	v_or_b32_e32 v0, s60, v0
	v_add_u32_e32 v11, 20, v9
	v_cndmask_b32_e64 v0, v11, v0, s[4:5]
	v_ashrrev_i32_e32 v1, 31, v0
	v_lshlrev_b64 v[0:1], 11, v[0:1]
	v_lshl_add_u64 v[106:107], v[4:5], 0, v[0:1]
	v_lshl_add_u64 v[0:1], v[106:107], 1, s[48:49]
	global_load_dwordx4 v[44:47], v[0:1], off
	v_bitop3_b32 v12, v10, v64, 15 bitop3:0x6c
	v_lshl_add_u32 v12, v12, 4, v8
	ds_read_b128 v[132:135], v12 offset:5120
	v_add_u32_e32 v10, 24, v65
	v_and_b32_e32 v0, 15, v10
	v_or_b32_e32 v0, s60, v0
	v_add_u32_e32 v11, 24, v9
	v_cndmask_b32_e64 v0, v11, v0, s[4:5]
	v_ashrrev_i32_e32 v1, 31, v0
	v_lshlrev_b64 v[0:1], 11, v[0:1]
	v_lshl_add_u64 v[108:109], v[4:5], 0, v[0:1]
	v_lshl_add_u64 v[0:1], v[108:109], 1, s[48:49]
	global_load_dwordx4 v[48:51], v[0:1], off
	v_bitop3_b32 v12, v10, v64, 15 bitop3:0x6c
	v_lshl_add_u32 v12, v12, 4, v8
	ds_read_b128 v[136:139], v12 offset:6144
	v_add_u32_e32 v10, 28, v65
	v_and_b32_e32 v0, 15, v10
	v_or_b32_e32 v0, s60, v0
	v_add_u32_e32 v11, 28, v9
	v_cndmask_b32_e64 v0, v11, v0, s[4:5]
	v_ashrrev_i32_e32 v1, 31, v0
	v_lshlrev_b64 v[0:1], 11, v[0:1]
	v_lshl_add_u64 v[110:111], v[4:5], 0, v[0:1]
	v_lshl_add_u64 v[0:1], v[110:111], 1, s[48:49]
	global_load_dwordx4 v[52:55], v[0:1], off
	v_bitop3_b32 v12, v10, v64, 15 bitop3:0x6c
	v_lshl_add_u32 v12, v12, 4, v8
	ds_read_b128 v[140:143], v12 offset:7168
	s_waitcnt lgkmcnt(7)
	v_lshlrev_b32_e32 v16, 16, v112
	v_and_b32_e32 v112, 0xffff0000, v112
	v_lshlrev_b32_e32 v17, 16, v113
	v_and_b32_e32 v113, 0xffff0000, v113
	v_lshlrev_b32_e32 v18, 16, v114
	v_and_b32_e32 v114, 0xffff0000, v114
	v_lshlrev_b32_e32 v19, 16, v115
	v_and_b32_e32 v115, 0xffff0000, v115
	s_waitcnt vmcnt(7)
	v_lshlrev_b32_e32 v20, 16, v24
	v_and_b32_e32 v24, 0xffff0000, v24
	v_lshlrev_b32_e32 v21, 16, v25
	v_and_b32_e32 v25, 0xffff0000, v25
	v_lshlrev_b32_e32 v22, 16, v26
	v_and_b32_e32 v26, 0xffff0000, v26
	v_lshlrev_b32_e32 v23, 16, v27
	v_and_b32_e32 v27, 0xffff0000, v27
	v_mul_f32_e32 v0, v112, v24
	v_mul_f32_e32 v1, v113, v25
	v_mul_f32_e32 v2, v114, v26
	v_mul_f32_e32 v3, v115, v27
	v_mul_f32_e32 v16, v16, v20
	v_mul_f32_e32 v17, v17, v21
	v_mul_f32_e32 v18, v18, v22
	v_mul_f32_e32 v19, v19, v23
	v_cvt_pk_bf16_f32 v0, v16, v0
	v_cvt_pk_bf16_f32 v1, v17, v1
	v_cvt_pk_bf16_f32 v2, v18, v2
	v_cvt_pk_bf16_f32 v3, v19, v3
	v_add_u32_e32 v10, 0, v65
	v_cmp_lt_i32_e32 vcc, 15, v10
	s_or_b64 s[6:7], s[56:57], vcc
	s_and_b64 s[6:7], s[4:5], s[6:7]
	s_xor_b64 s[36:37], s[6:7], -1
	s_and_saveexec_b64 s[6:7], s[36:37]
	s_cbranch_execz .Lattn_ep_skip0
	v_lshl_add_u64 v[6:7], v[96:97], 1, s[16:17]
	global_store_dwordx4 v[6:7], v[0:3], off sc1
.Lattn_ep_skip0:
	s_or_b64 exec, exec, s[6:7]
	s_waitcnt lgkmcnt(6)
	v_lshlrev_b32_e32 v16, 16, v116
	v_and_b32_e32 v116, 0xffff0000, v116
	v_lshlrev_b32_e32 v17, 16, v117
	v_and_b32_e32 v117, 0xffff0000, v117
	v_lshlrev_b32_e32 v18, 16, v118
	v_and_b32_e32 v118, 0xffff0000, v118
	v_lshlrev_b32_e32 v19, 16, v119
	v_and_b32_e32 v119, 0xffff0000, v119
	s_waitcnt vmcnt(6)
	v_lshlrev_b32_e32 v20, 16, v28
	v_and_b32_e32 v28, 0xffff0000, v28
	v_lshlrev_b32_e32 v21, 16, v29
	v_and_b32_e32 v29, 0xffff0000, v29
	v_lshlrev_b32_e32 v22, 16, v30
	v_and_b32_e32 v30, 0xffff0000, v30
	v_lshlrev_b32_e32 v23, 16, v31
	v_and_b32_e32 v31, 0xffff0000, v31
	v_mul_f32_e32 v0, v116, v28
	v_mul_f32_e32 v1, v117, v29
	v_mul_f32_e32 v2, v118, v30
	v_mul_f32_e32 v3, v119, v31
	v_mul_f32_e32 v16, v16, v20
	v_mul_f32_e32 v17, v17, v21
	v_mul_f32_e32 v18, v18, v22
	v_mul_f32_e32 v19, v19, v23
	v_cvt_pk_bf16_f32 v0, v16, v0
	v_cvt_pk_bf16_f32 v1, v17, v1
	v_cvt_pk_bf16_f32 v2, v18, v2
	v_cvt_pk_bf16_f32 v3, v19, v3
	v_add_u32_e32 v10, 4, v65
	v_cmp_lt_i32_e32 vcc, 15, v10
	s_or_b64 s[6:7], s[56:57], vcc
	s_and_b64 s[6:7], s[4:5], s[6:7]
	s_xor_b64 s[36:37], s[6:7], -1
	s_and_saveexec_b64 s[6:7], s[36:37]
	s_cbranch_execz .Lattn_ep_skip1
	v_lshl_add_u64 v[6:7], v[98:99], 1, s[16:17]
	global_store_dwordx4 v[6:7], v[0:3], off sc1
; __device__ __forceinline__ unsigned cvt_pk_bf16(float lo, float hi) { unsigned r; asm volatile("v_cvt_pk_bf16_f32 %0, %1, %2" : "=v"(r) : "v"(lo), "v"(hi)); return r; }
; #define LAS __attribute__((address_space(3)))
; __device__ __forceinline__ void attn_phase(LAS unsigned char* lds, bf16_t* Qb, const bf16_t* KVb, const bf16_t* GZ, const float* sinkp) {
;     ...
;         for (int it = 0; it < 8; ++it) {
;             const int rr = cro + 4 * it, grow = mu ? NREAL + seq * 16 + (rr & 15) : row0 + rr;
;             const u32x4 ovv = *(const LAS u32x4*)(Wl + rr * 256 + ((cho ^ (rr & 15)) << 4));
;             const size_t goff = (size_t)grow * 2048 + head * 128 + cho * 8;
;             const u32x4 gz = *(const u32x4*)(GZ + goff);
;             float fo[8], fg[8]; unpack8(ovv, fo); unpack8(gz, fg);
;             u32x4 res; res.x = cvt_pk_bf16(fo[0] * fg[0], fo[1] * fg[1]); res.y = cvt_pk_bf16(fo[2] * fg[2], fo[3] * fg[3]); res.z = cvt_pk_bf16(fo[4] * fg[4], fo[5] * fg[5]); res.w = cvt_pk_bf16(fo[6] * fg[6], fo[7] * fg[7]);
;             if (!mu || (w < 4 && rr < 16)) *(u32x4*)(Qb + goff) = res;
;         }
.Lattn_ep_skip1:
	s_or_b64 exec, exec, s[6:7]
	s_waitcnt lgkmcnt(5)
	v_lshlrev_b32_e32 v16, 16, v120
	v_and_b32_e32 v120, 0xffff0000, v120
	v_lshlrev_b32_e32 v17, 16, v121
	v_and_b32_e32 v121, 0xffff0000, v121
	v_lshlrev_b32_e32 v18, 16, v122
	v_and_b32_e32 v122, 0xffff0000, v122
	v_lshlrev_b32_e32 v19, 16, v123
	v_and_b32_e32 v123, 0xffff0000, v123
	s_waitcnt vmcnt(5)
	v_lshlrev_b32_e32 v20, 16, v32
	v_and_b32_e32 v32, 0xffff0000, v32
	v_lshlrev_b32_e32 v21, 16, v33
	v_and_b32_e32 v33, 0xffff0000, v33
	v_lshlrev_b32_e32 v22, 16, v34
	v_and_b32_e32 v34, 0xffff0000, v34
	v_lshlrev_b32_e32 v23, 16, v35
	v_and_b32_e32 v35, 0xffff0000, v35
	v_mul_f32_e32 v0, v120, v32
	v_mul_f32_e32 v1, v121, v33
	v_mul_f32_e32 v2, v122, v34
	v_mul_f32_e32 v3, v123, v35
	v_mul_f32_e32 v16, v16, v20
	v_mul_f32_e32 v17, v17, v21
	v_mul_f32_e32 v18, v18, v22
	v_mul_f32_e32 v19, v19, v23
	v_cvt_pk_bf16_f32 v0, v16, v0
	v_cvt_pk_bf16_f32 v1, v17, v1
	v_cvt_pk_bf16_f32 v2, v18, v2
	v_cvt_pk_bf16_f32 v3, v19, v3
	v_add_u32_e32 v10, 8, v65
	v_cmp_lt_i32_e32 vcc, 15, v10
	s_or_b64 s[6:7], s[56:57], vcc
	s_and_b64 s[6:7], s[4:5], s[6:7]
	s_xor_b64 s[36:37], s[6:7], -1
	s_and_saveexec_b64 s[6:7], s[36:37]
	s_cbranch_execz .Lattn_ep_skip2
	v_lshl_add_u64 v[6:7], v[100:101], 1, s[16:17]
	global_store_dwordx4 v[6:7], v[0:3], off sc1
.Lattn_ep_skip2:
	s_or_b64 exec, exec, s[6:7]
	s_waitcnt lgkmcnt(4)
	v_lshlrev_b32_e32 v16, 16, v124
	v_and_b32_e32 v124, 0xffff0000, v124
	v_lshlrev_b32_e32 v17, 16, v125
	v_and_b32_e32 v125, 0xffff0000, v125
	v_lshlrev_b32_e32 v18, 16, v126
	v_and_b32_e32 v126, 0xffff0000, v126
	v_lshlrev_b32_e32 v19, 16, v127
	v_and_b32_e32 v127, 0xffff0000, v127
	s_waitcnt vmcnt(4)
	v_lshlrev_b32_e32 v20, 16, v36
	v_and_b32_e32 v36, 0xffff0000, v36
	v_lshlrev_b32_e32 v21, 16, v37
	v_and_b32_e32 v37, 0xffff0000, v37
	v_lshlrev_b32_e32 v22, 16, v38
	v_and_b32_e32 v38, 0xffff0000, v38
	v_lshlrev_b32_e32 v23, 16, v39
	v_and_b32_e32 v39, 0xffff0000, v39
	v_mul_f32_e32 v0, v124, v36
	v_mul_f32_e32 v1, v125, v37
	v_mul_f32_e32 v2, v126, v38
	v_mul_f32_e32 v3, v127, v39
	v_mul_f32_e32 v16, v16, v20
	v_mul_f32_e32 v17, v17, v21
	v_mul_f32_e32 v18, v18, v22
	v_mul_f32_e32 v19, v19, v23
	v_cvt_pk_bf16_f32 v0, v16, v0
	v_cvt_pk_bf16_f32 v1, v17, v1
	v_cvt_pk_bf16_f32 v2, v18, v2
	v_cvt_pk_bf16_f32 v3, v19, v3
	v_add_u32_e32 v10, 12, v65
	v_cmp_lt_i32_e32 vcc, 15, v10
	s_or_b64 s[6:7], s[56:57], vcc
	s_and_b64 s[6:7], s[4:5], s[6:7]
	s_xor_b64 s[36:37], s[6:7], -1
	s_and_saveexec_b64 s[6:7], s[36:37]
	s_cbranch_execz .Lattn_ep_skip3
	v_lshl_add_u64 v[6:7], v[102:103], 1, s[16:17]
	global_store_dwordx4 v[6:7], v[0:3], off sc1
.Lattn_ep_skip3:
	s_or_b64 exec, exec, s[6:7]
	s_waitcnt lgkmcnt(3)
	v_lshlrev_b32_e32 v16, 16, v128
	v_and_b32_e32 v128, 0xffff0000, v128
	v_lshlrev_b32_e32 v17, 16, v129
	v_and_b32_e32 v129, 0xffff0000, v129
	v_lshlrev_b32_e32 v18, 16, v130
	v_and_b32_e32 v130, 0xffff0000, v130
	v_lshlrev_b32_e32 v19, 16, v131
	v_and_b32_e32 v131, 0xffff0000, v131
	s_waitcnt vmcnt(3)
	v_lshlrev_b32_e32 v20, 16, v40
	v_and_b32_e32 v40, 0xffff0000, v40
	v_lshlrev_b32_e32 v21, 16, v41
	v_and_b32_e32 v41, 0xffff0000, v41
	v_lshlrev_b32_e32 v22, 16, v42
	v_and_b32_e32 v42, 0xffff0000, v42
	v_lshlrev_b32_e32 v23, 16, v43
	v_and_b32_e32 v43, 0xffff0000, v43
	v_mul_f32_e32 v0, v128, v40
	v_mul_f32_e32 v1, v129, v41
	v_mul_f32_e32 v2, v130, v42
	v_mul_f32_e32 v3, v131, v43
	v_mul_f32_e32 v16, v16, v20
	v_mul_f32_e32 v17, v17, v21
	v_mul_f32_e32 v18, v18, v22
	v_mul_f32_e32 v19, v19, v23
	v_cvt_pk_bf16_f32 v0, v16, v0
	v_cvt_pk_bf16_f32 v1, v17, v1
	v_cvt_pk_bf16_f32 v2, v18, v2
	v_cvt_pk_bf16_f32 v3, v19, v3
	v_add_u32_e32 v10, 16, v65
	v_cmp_lt_i32_e32 vcc, 15, v10
	s_or_b64 s[6:7], s[56:57], vcc
	s_and_b64 s[6:7], s[4:5], s[6:7]
	s_xor_b64 s[36:37], s[6:7], -1
	s_and_saveexec_b64 s[6:7], s[36:37]
	s_cbranch_execz .Lattn_ep_skip4
	v_lshl_add_u64 v[6:7], v[104:105], 1, s[16:17]
	global_store_dwordx4 v[6:7], v[0:3], off sc1
; __device__ __forceinline__ unsigned cvt_pk_bf16(float lo, float hi) { unsigned r; asm volatile("v_cvt_pk_bf16_f32 %0, %1, %2" : "=v"(r) : "v"(lo), "v"(hi)); return r; }
; #define LAS __attribute__((address_space(3)))
; __device__ __forceinline__ void attn_phase(LAS unsigned char* lds, bf16_t* Qb, const bf16_t* KVb, const bf16_t* GZ, const float* sinkp) {
;     ...
;         for (int it = 0; it < 8; ++it) {
;             const int rr = cro + 4 * it, grow = mu ? NREAL + seq * 16 + (rr & 15) : row0 + rr;
;             const u32x4 ovv = *(const LAS u32x4*)(Wl + rr * 256 + ((cho ^ (rr & 15)) << 4));
;             const size_t goff = (size_t)grow * 2048 + head * 128 + cho * 8;
;             const u32x4 gz = *(const u32x4*)(GZ + goff);
;             float fo[8], fg[8]; unpack8(ovv, fo); unpack8(gz, fg);
;             u32x4 res; res.x = cvt_pk_bf16(fo[0] * fg[0], fo[1] * fg[1]); res.y = cvt_pk_bf16(fo[2] * fg[2], fo[3] * fg[3]); res.z = cvt_pk_bf16(fo[4] * fg[4], fo[5] * fg[5]); res.w = cvt_pk_bf16(fo[6] * fg[6], fo[7] * fg[7]);
;             if (!mu || (w < 4 && rr < 16)) *(u32x4*)(Qb + goff) = res;
;         }
.Lattn_ep_skip4:
	s_or_b64 exec, exec, s[6:7]
	s_waitcnt lgkmcnt(2)
	v_lshlrev_b32_e32 v16, 16, v132
	v_and_b32_e32 v132, 0xffff0000, v132
	v_lshlrev_b32_e32 v17, 16, v133
	v_and_b32_e32 v133, 0xffff0000, v133
	v_lshlrev_b32_e32 v18, 16, v134
	v_and_b32_e32 v134, 0xffff0000, v134
	v_lshlrev_b32_e32 v19, 16, v135
	v_and_b32_e32 v135, 0xffff0000, v135
	s_waitcnt vmcnt(2)
	v_lshlrev_b32_e32 v20, 16, v44
	v_and_b32_e32 v44, 0xffff0000, v44
	v_lshlrev_b32_e32 v21, 16, v45
	v_and_b32_e32 v45, 0xffff0000, v45
	v_lshlrev_b32_e32 v22, 16, v46
	v_and_b32_e32 v46, 0xffff0000, v46
	v_lshlrev_b32_e32 v23, 16, v47
	v_and_b32_e32 v47, 0xffff0000, v47
	v_mul_f32_e32 v0, v132, v44
	v_mul_f32_e32 v1, v133, v45
	v_mul_f32_e32 v2, v134, v46
	v_mul_f32_e32 v3, v135, v47
	v_mul_f32_e32 v16, v16, v20
	v_mul_f32_e32 v17, v17, v21
	v_mul_f32_e32 v18, v18, v22
	v_mul_f32_e32 v19, v19, v23
	v_cvt_pk_bf16_f32 v0, v16, v0
	v_cvt_pk_bf16_f32 v1, v17, v1
	v_cvt_pk_bf16_f32 v2, v18, v2
	v_cvt_pk_bf16_f32 v3, v19, v3
	v_add_u32_e32 v10, 20, v65
	v_cmp_lt_i32_e32 vcc, 15, v10
	s_or_b64 s[6:7], s[56:57], vcc
	s_and_b64 s[6:7], s[4:5], s[6:7]
	s_xor_b64 s[36:37], s[6:7], -1
	s_and_saveexec_b64 s[6:7], s[36:37]
	s_cbranch_execz .Lattn_ep_skip5
	v_lshl_add_u64 v[6:7], v[106:107], 1, s[16:17]
	global_store_dwordx4 v[6:7], v[0:3], off sc1
.Lattn_ep_skip5:
	s_or_b64 exec, exec, s[6:7]
	s_waitcnt lgkmcnt(1)
	v_lshlrev_b32_e32 v16, 16, v136
	v_and_b32_e32 v136, 0xffff0000, v136
	v_lshlrev_b32_e32 v17, 16, v137
	v_and_b32_e32 v137, 0xffff0000, v137
	v_lshlrev_b32_e32 v18, 16, v138
	v_and_b32_e32 v138, 0xffff0000, v138
	v_lshlrev_b32_e32 v19, 16, v139
	v_and_b32_e32 v139, 0xffff0000, v139
	s_waitcnt vmcnt(1)
	v_lshlrev_b32_e32 v20, 16, v48
	v_and_b32_e32 v48, 0xffff0000, v48
	v_lshlrev_b32_e32 v21, 16, v49
	v_and_b32_e32 v49, 0xffff0000, v49
	v_lshlrev_b32_e32 v22, 16, v50
	v_and_b32_e32 v50, 0xffff0000, v50
	v_lshlrev_b32_e32 v23, 16, v51
	v_and_b32_e32 v51, 0xffff0000, v51
	v_mul_f32_e32 v0, v136, v48
	v_mul_f32_e32 v1, v137, v49
	v_mul_f32_e32 v2, v138, v50
	v_mul_f32_e32 v3, v139, v51
	v_mul_f32_e32 v16, v16, v20
	v_mul_f32_e32 v17, v17, v21
	v_mul_f32_e32 v18, v18, v22
	v_mul_f32_e32 v19, v19, v23
	v_cvt_pk_bf16_f32 v0, v16, v0
	v_cvt_pk_bf16_f32 v1, v17, v1
	v_cvt_pk_bf16_f32 v2, v18, v2
	v_cvt_pk_bf16_f32 v3, v19, v3
	v_add_u32_e32 v10, 24, v65
	v_cmp_lt_i32_e32 vcc, 15, v10
	s_or_b64 s[6:7], s[56:57], vcc
	s_and_b64 s[6:7], s[4:5], s[6:7]
	s_xor_b64 s[36:37], s[6:7], -1
	s_and_saveexec_b64 s[6:7], s[36:37]
	s_cbranch_execz .Lattn_ep_skip6
	v_lshl_add_u64 v[6:7], v[108:109], 1, s[16:17]
	global_store_dwordx4 v[6:7], v[0:3], off sc1
.Lattn_ep_skip6:
	s_or_b64 exec, exec, s[6:7]
	s_waitcnt lgkmcnt(0)
	v_lshlrev_b32_e32 v16, 16, v140
	v_and_b32_e32 v140, 0xffff0000, v140
	v_lshlrev_b32_e32 v17, 16, v141
	v_and_b32_e32 v141, 0xffff0000, v141
	v_lshlrev_b32_e32 v18, 16, v142
	v_and_b32_e32 v142, 0xffff0000, v142
	v_lshlrev_b32_e32 v19, 16, v143
	v_and_b32_e32 v143, 0xffff0000, v143
	s_waitcnt vmcnt(0)
	v_lshlrev_b32_e32 v20, 16, v52
	v_and_b32_e32 v52, 0xffff0000, v52
	v_lshlrev_b32_e32 v21, 16, v53
	v_and_b32_e32 v53, 0xffff0000, v53
	v_lshlrev_b32_e32 v22, 16, v54
	v_and_b32_e32 v54, 0xffff0000, v54
	v_lshlrev_b32_e32 v23, 16, v55
	v_and_b32_e32 v55, 0xffff0000, v55
	v_mul_f32_e32 v0, v140, v52
	v_mul_f32_e32 v1, v141, v53
	v_mul_f32_e32 v2, v142, v54
	v_mul_f32_e32 v3, v143, v55
	v_mul_f32_e32 v16, v16, v20
	v_mul_f32_e32 v17, v17, v21
	v_mul_f32_e32 v18, v18, v22
	v_mul_f32_e32 v19, v19, v23
	v_cvt_pk_bf16_f32 v0, v16, v0
	v_cvt_pk_bf16_f32 v1, v17, v1
	v_cvt_pk_bf16_f32 v2, v18, v2
	v_cvt_pk_bf16_f32 v3, v19, v3
	v_add_u32_e32 v10, 28, v65
	v_cmp_lt_i32_e32 vcc, 15, v10
	s_or_b64 s[6:7], s[56:57], vcc
	s_and_b64 s[6:7], s[4:5], s[6:7]
	s_xor_b64 s[36:37], s[6:7], -1
	s_and_saveexec_b64 s[6:7], s[36:37]
	s_cbranch_execz .Lattn_ep_skip7
	v_lshl_add_u64 v[6:7], v[110:111], 1, s[16:17]
	global_store_dwordx4 v[6:7], v[0:3], off sc1

; __device__ __forceinline__ unsigned cvt_pk_bf16(float lo, float hi) { unsigned r; asm volatile("v_cvt_pk_bf16_f32 %0, %1, %2" : "=v"(r) : "v"(lo), "v"(hi)); return r; }
;     __device__ __forceinline__ void operator()(const f32x4 (&acc)[2][2][4][2], const Unit& u, int wr, int wc, int fr, int fq) const {
;         const int r0 = u.pm * BM + wr * 64 + fr, c0 = u.pn * BM + 32 * wc + 8 * fq;
;         u32x4 hold[2][4][2];
; #pragma unroll
;         for (int ai = 0; ai < 2; ++ai)
; #pragma unroll
;             for (int m = 0; m < 4; ++m)
; #pragma unroll
;                 for (int bj = 0; bj < 2; ++bj) hold[ai][m][bj] = *(const u32x4*)(HB + (size_t)(r0 + ai * HALF + m * 16) * 2048 + c0 + bj * HALF);
; #pragma unroll
;         for (int ai = 0; ai < 2; ++ai)
; #pragma unroll
;             for (int m = 0; m < 4; ++m) {
;                 const int r = r0 + ai * HALF + m * 16;
;                 const bool valid = r < NREAL + NMETA;
;                 float ssum = 0.f;
; #pragma unroll
;                 for (int bj = 0; bj < 2; ++bj) {
;                     const u32x4 hv = hold[ai][m][bj];
;                     f32x4 h0 = {__uint_as_float(hv.x << 16), __uint_as_float(hv.x & 0xffff0000u), __uint_as_float(hv.y << 16), __uint_as_float(hv.y & 0xffff0000u)};
;                     f32x4 h1 = {__uint_as_float(hv.z << 16), __uint_as_float(hv.z & 0xffff0000u), __uint_as_float(hv.w << 16), __uint_as_float(hv.w & 0xffff0000u)};
;                     h0 += acc[ai][bj][m][0]; h1 += acc[ai][bj][m][1];
;                     const int col0 = c0 + bj * HALF;
;                     u32x4 w; w.x = cvt_pk_bf16(h0[0], h0[1]); w.y = cvt_pk_bf16(h0[2], h0[3]); w.z = cvt_pk_bf16(h1[0], h1[1]); w.w = cvt_pk_bf16(h1[2], h1[3]);
;                     if (valid) *(u32x4*)(HB + (size_t)r * 2048 + col0) = w;
.LBB0_208:
	v_lshl_add_u32 v202, s66, 8, v237
	v_lshl_or_b32 v200, s8, 8, v239
	v_ashrrev_i32_e32 v201, 31, v200
	v_ashrrev_i32_e32 v203, 31, v202
	v_or_b32_e32 v222, 16, v202
	v_lshl_add_u64 v[80:81], v[200:201], 1, s[34:35]
	v_lshlrev_b64 v[242:243], 12, v[202:203]
	v_ashrrev_i32_e32 v223, 31, v222
	v_or_b32_e32 v218, 32, v202
	v_lshl_add_u64 v[82:83], v[80:81], 0, v[242:243]
	v_lshlrev_b64 v[220:221], 12, v[222:223]
	v_ashrrev_i32_e32 v219, 31, v218
	v_or_b32_e32 v214, 48, v202
	global_load_dwordx4 v[228:231], v[82:83], off
	global_load_dwordx4 v[184:187], v[82:83], off offset:256
	v_lshl_add_u64 v[82:83], v[80:81], 0, v[220:221]
	v_lshlrev_b64 v[216:217], 12, v[218:219]
	v_ashrrev_i32_e32 v215, 31, v214
	s_mov_b64 s[8:9], 0x80000
	global_load_dwordx4 v[180:183], v[82:83], off
	global_load_dwordx4 v[176:179], v[82:83], off offset:256
	v_lshl_add_u64 v[82:83], v[80:81], 0, v[216:217]
	v_lshlrev_b64 v[212:213], 12, v[214:215]
	v_lshl_add_u64 v[210:211], v[242:243], 0, s[8:9]
	s_mov_b64 s[8:9], 0x90000
	global_load_dwordx4 v[172:175], v[82:83], off
	global_load_dwordx4 v[168:171], v[82:83], off offset:256
	v_lshl_add_u64 v[82:83], v[80:81], 0, v[212:213]
	v_lshl_add_u64 v[208:209], v[242:243], 0, s[8:9]
	s_mov_b64 s[8:9], 0xa0000
	global_load_dwordx4 v[164:167], v[82:83], off
	global_load_dwordx4 v[160:163], v[82:83], off offset:256
	v_lshl_add_u64 v[82:83], v[80:81], 0, v[210:211]
	v_lshl_add_u64 v[206:207], v[242:243], 0, s[8:9]
	s_mov_b64 s[8:9], 0xb0000
	global_load_dwordx4 v[156:159], v[82:83], off
	global_load_dwordx4 v[152:155], v[82:83], off offset:256
	v_lshl_add_u64 v[82:83], v[80:81], 0, v[208:209]
	v_lshl_add_u64 v[204:205], v[242:243], 0, s[8:9]
	global_load_dwordx4 v[132:135], v[82:83], off
	global_load_dwordx4 v[128:131], v[82:83], off offset:256
	v_lshl_add_u64 v[82:83], v[80:81], 0, v[206:207]
	v_lshl_add_u64 v[80:81], v[80:81], 0, v[204:205]
	global_load_dwordx4 v[108:111], v[82:83], off
	global_load_dwordx4 v[104:107], v[82:83], off offset:256
	global_load_dwordx4 v[88:91], v[80:81], off
	s_nop 0
	global_load_dwordx4 v[80:83], v[80:81], off offset:256
	v_lshl_add_u64 v[242:243], s[34:35], 0, v[242:243]
	v_cmp_gt_i32_e32 vcc, s84, v202
	s_waitcnt vmcnt(0)
	v_lshlrev_b32_e32 v244, 16, v228
	v_and_b32_e32 v245, 0xffff0000, v228
	v_lshlrev_b32_e32 v228, 16, v229
	v_and_b32_e32 v229, 0xffff0000, v229
	v_lshlrev_b32_e32 v246, 16, v230
	v_and_b32_e32 v247, 0xffff0000, v230
	v_lshlrev_b32_e32 v230, 16, v231
	v_and_b32_e32 v231, 0xffff0000, v231
	v_pk_add_f32 v[148:149], v[148:149], v[244:245]
	v_pk_add_f32 v[150:151], v[150:151], v[228:229]
	v_pk_add_f32 v[228:229], v[146:147], v[230:231]
	v_pk_add_f32 v[146:147], v[144:145], v[246:247]
	v_cvt_pk_bf16_f32 v144, v148, v149
	v_lshl_add_u64 v[148:149], v[200:201], 1, v[242:243]
	v_cvt_pk_bf16_f32 v145, v150, v151
	v_cvt_pk_bf16_f32 v146, v146, v147
	v_cvt_pk_bf16_f32 v147, v228, v229
	s_and_saveexec_b64 s[8:9], vcc
	s_cbranch_execz .LBB0_210
	global_store_dwordx4 v[148:149], v[144:147], off sc1
.LBB0_210:
	s_or_b64 exec, exec, s[8:9]
	v_lshlrev_b32_e32 v150, 16, v184
	v_and_b32_e32 v151, 0xffff0000, v184
	v_lshlrev_b32_e32 v228, 16, v186
	v_and_b32_e32 v229, 0xffff0000, v186
	v_lshlrev_b32_e32 v186, 16, v187
	v_and_b32_e32 v187, 0xffff0000, v187
	v_lshlrev_b32_e32 v184, 16, v185
	v_and_b32_e32 v185, 0xffff0000, v185
	v_pk_add_f32 v[140:141], v[140:141], v[150:151]
	v_pk_add_f32 v[150:151], v[138:139], v[186:187]
	v_pk_add_f32 v[138:139], v[136:137], v[228:229]
	v_pk_add_f32 v[142:143], v[142:143], v[184:185]
	v_cvt_pk_bf16_f32 v136, v140, v141
	s_nop 0
	v_cvt_pk_bf16_f32 v137, v142, v143
	v_cvt_pk_bf16_f32 v138, v138, v139
	v_cvt_pk_bf16_f32 v139, v150, v151
	s_and_saveexec_b64 s[8:9], vcc
	s_cbranch_execz .LBB0_212
	global_store_dwordx4 v[148:149], v[136:139], off offset:256 sc1

; __device__ __forceinline__ unsigned cvt_pk_bf16(float lo, float hi) { unsigned r; asm volatile("v_cvt_pk_bf16_f32 %0, %1, %2" : "=v"(r) : "v"(lo), "v"(hi)); return r; }
;     __device__ __forceinline__ void operator()(const f32x4 (&acc)[2][2][4][2], const Unit& u, int wr, int wc, int fr, int fq) const {
;     ...
;         for (int ai = 0; ai < 2; ++ai)
; #pragma unroll
;             for (int m = 0; m < 4; ++m) {
;                 const int r = r0 + ai * HALF + m * 16;
;                 const bool valid = r < NREAL + NMETA;
;                 float ssum = 0.f;
; #pragma unroll
;                 for (int bj = 0; bj < 2; ++bj) {
;                     const u32x4 hv = hold[ai][m][bj];
;                     f32x4 h0 = {__uint_as_float(hv.x << 16), __uint_as_float(hv.x & 0xffff0000u), __uint_as_float(hv.y << 16), __uint_as_float(hv.y & 0xffff0000u)};
;                     f32x4 h1 = {__uint_as_float(hv.z << 16), __uint_as_float(hv.z & 0xffff0000u), __uint_as_float(hv.w << 16), __uint_as_float(hv.w & 0xffff0000u)};
;                     h0 += acc[ai][bj][m][0]; h1 += acc[ai][bj][m][1];
;                     const int col0 = c0 + bj * HALF;
;                     u32x4 w; w.x = cvt_pk_bf16(h0[0], h0[1]); w.y = cvt_pk_bf16(h0[2], h0[3]); w.z = cvt_pk_bf16(h1[0], h1[1]); w.w = cvt_pk_bf16(h1[2], h1[3]);
;                     if (valid) *(u32x4*)(HB + (size_t)r * 2048 + col0) = w;
.LBB0_214:
	s_or_b64 exec, exec, s[8:9]
	v_lshlrev_b32_e32 v140, 16, v180
	s_waitcnt lgkmcnt(0)
	v_and_b32_e32 v141, 0xffff0000, v180
	v_lshlrev_b32_e32 v144, 16, v182
	v_and_b32_e32 v145, 0xffff0000, v182
	v_lshlrev_b32_e32 v146, 16, v183
	v_and_b32_e32 v147, 0xffff0000, v183
	v_pk_add_f32 v[124:125], v[124:125], v[140:141]
	v_pk_add_f32 v[140:141], v[122:123], v[146:147]
	v_pk_add_f32 v[122:123], v[120:121], v[144:145]
	v_cvt_pk_bf16_f32 v120, v124, v125
	v_lshl_add_u64 v[124:125], s[34:35], 0, v[220:221]
	v_cmp_gt_i32_e32 vcc, s84, v222
	v_lshlrev_b32_e32 v142, 16, v181
	v_and_b32_e32 v143, 0xffff0000, v181
	v_lshl_add_u64 v[124:125], v[200:201], 1, v[124:125]
	v_pk_add_f32 v[126:127], v[126:127], v[142:143]
	s_nop 0
	v_cvt_pk_bf16_f32 v121, v126, v127
	v_cvt_pk_bf16_f32 v122, v122, v123
	v_cvt_pk_bf16_f32 v123, v140, v141
	s_and_saveexec_b64 s[8:9], vcc
	s_cbranch_execz .LBB0_216
	global_store_dwordx4 v[124:125], v[120:123], off sc1
.LBB0_216:
	s_or_b64 exec, exec, s[8:9]
	v_lshlrev_b32_e32 v126, 16, v176
	v_and_b32_e32 v127, 0xffff0000, v176
	v_lshlrev_b32_e32 v142, 16, v178
	v_and_b32_e32 v143, 0xffff0000, v178
	v_lshlrev_b32_e32 v144, 16, v179
	v_and_b32_e32 v145, 0xffff0000, v179
	v_lshlrev_b32_e32 v140, 16, v177
	v_and_b32_e32 v141, 0xffff0000, v177
	v_pk_add_f32 v[116:117], v[116:117], v[126:127]
	v_pk_add_f32 v[126:127], v[114:115], v[144:145]
	v_pk_add_f32 v[114:115], v[112:113], v[142:143]
	v_pk_add_f32 v[118:119], v[118:119], v[140:141]
	v_cvt_pk_bf16_f32 v112, v116, v117
	s_nop 0
	v_cvt_pk_bf16_f32 v113, v118, v119
	v_cvt_pk_bf16_f32 v114, v114, v115
	v_cvt_pk_bf16_f32 v115, v126, v127
	s_and_saveexec_b64 s[8:9], vcc
	s_cbranch_execz .LBB0_218
	global_store_dwordx4 v[124:125], v[112:115], off offset:256 sc1

; __device__ __forceinline__ unsigned cvt_pk_bf16(float lo, float hi) { unsigned r; asm volatile("v_cvt_pk_bf16_f32 %0, %1, %2" : "=v"(r) : "v"(lo), "v"(hi)); return r; }
;     __device__ __forceinline__ void operator()(const f32x4 (&acc)[2][2][4][2], const Unit& u, int wr, int wc, int fr, int fq) const {
;     ...
;         for (int ai = 0; ai < 2; ++ai)
; #pragma unroll
;             for (int m = 0; m < 4; ++m) {
;                 const int r = r0 + ai * HALF + m * 16;
;                 const bool valid = r < NREAL + NMETA;
;                 float ssum = 0.f;
; #pragma unroll
;                 for (int bj = 0; bj < 2; ++bj) {
;                     const u32x4 hv = hold[ai][m][bj];
;                     f32x4 h0 = {__uint_as_float(hv.x << 16), __uint_as_float(hv.x & 0xffff0000u), __uint_as_float(hv.y << 16), __uint_as_float(hv.y & 0xffff0000u)};
;                     f32x4 h1 = {__uint_as_float(hv.z << 16), __uint_as_float(hv.z & 0xffff0000u), __uint_as_float(hv.w << 16), __uint_as_float(hv.w & 0xffff0000u)};
;                     h0 += acc[ai][bj][m][0]; h1 += acc[ai][bj][m][1];
;                     const int col0 = c0 + bj * HALF;
;                     u32x4 w; w.x = cvt_pk_bf16(h0[0], h0[1]); w.y = cvt_pk_bf16(h0[2], h0[3]); w.z = cvt_pk_bf16(h1[0], h1[1]); w.w = cvt_pk_bf16(h1[2], h1[3]);
;                     if (valid) *(u32x4*)(HB + (size_t)r * 2048 + col0) = w;
.LBB0_220:
	s_or_b64 exec, exec, s[8:9]
	v_lshlrev_b32_e32 v112, 16, v172
	s_waitcnt lgkmcnt(0)
	v_and_b32_e32 v113, 0xffff0000, v172
	v_lshlrev_b32_e32 v116, 16, v174
	v_and_b32_e32 v117, 0xffff0000, v174
	v_lshlrev_b32_e32 v118, 16, v175
	v_and_b32_e32 v119, 0xffff0000, v175
	v_pk_add_f32 v[100:101], v[100:101], v[112:113]
	v_pk_add_f32 v[112:113], v[98:99], v[118:119]
	v_pk_add_f32 v[98:99], v[96:97], v[116:117]
	v_cvt_pk_bf16_f32 v96, v100, v101
	v_lshl_add_u64 v[100:101], s[34:35], 0, v[216:217]
	v_cmp_gt_i32_e32 vcc, s84, v218
	v_lshlrev_b32_e32 v114, 16, v173
	v_and_b32_e32 v115, 0xffff0000, v173
	v_lshl_add_u64 v[100:101], v[200:201], 1, v[100:101]
	v_pk_add_f32 v[102:103], v[102:103], v[114:115]
	s_nop 0
	v_cvt_pk_bf16_f32 v97, v102, v103
	v_cvt_pk_bf16_f32 v98, v98, v99
	v_cvt_pk_bf16_f32 v99, v112, v113
	s_and_saveexec_b64 s[8:9], vcc
	s_cbranch_execz .LBB0_222
	global_store_dwordx4 v[100:101], v[96:99], off sc1
.LBB0_222:
	s_or_b64 exec, exec, s[8:9]
	v_lshlrev_b32_e32 v102, 16, v168
	v_and_b32_e32 v103, 0xffff0000, v168
	v_lshlrev_b32_e32 v114, 16, v170
	v_and_b32_e32 v115, 0xffff0000, v170
	v_lshlrev_b32_e32 v116, 16, v171
	v_and_b32_e32 v117, 0xffff0000, v171
	v_lshlrev_b32_e32 v112, 16, v169
	v_and_b32_e32 v113, 0xffff0000, v169
	v_pk_add_f32 v[92:93], v[92:93], v[102:103]
	v_pk_add_f32 v[102:103], v[86:87], v[116:117]
	v_pk_add_f32 v[86:87], v[84:85], v[114:115]
	v_pk_add_f32 v[94:95], v[94:95], v[112:113]
	v_cvt_pk_bf16_f32 v84, v92, v93
	s_nop 0
	v_cvt_pk_bf16_f32 v85, v94, v95
	v_cvt_pk_bf16_f32 v86, v86, v87
	v_cvt_pk_bf16_f32 v87, v102, v103
	s_and_saveexec_b64 s[8:9], vcc
	s_cbranch_execz .LBB0_224
	global_store_dwordx4 v[100:101], v[84:87], off offset:256 sc1

; __device__ __forceinline__ unsigned cvt_pk_bf16(float lo, float hi) { unsigned r; asm volatile("v_cvt_pk_bf16_f32 %0, %1, %2" : "=v"(r) : "v"(lo), "v"(hi)); return r; }
;     __device__ __forceinline__ void operator()(const f32x4 (&acc)[2][2][4][2], const Unit& u, int wr, int wc, int fr, int fq) const {
;     ...
;         for (int ai = 0; ai < 2; ++ai)
; #pragma unroll
;             for (int m = 0; m < 4; ++m) {
;                 const int r = r0 + ai * HALF + m * 16;
;                 const bool valid = r < NREAL + NMETA;
;                 float ssum = 0.f;
; #pragma unroll
;                 for (int bj = 0; bj < 2; ++bj) {
;                     const u32x4 hv = hold[ai][m][bj];
;                     f32x4 h0 = {__uint_as_float(hv.x << 16), __uint_as_float(hv.x & 0xffff0000u), __uint_as_float(hv.y << 16), __uint_as_float(hv.y & 0xffff0000u)};
;                     f32x4 h1 = {__uint_as_float(hv.z << 16), __uint_as_float(hv.z & 0xffff0000u), __uint_as_float(hv.w << 16), __uint_as_float(hv.w & 0xffff0000u)};
;                     h0 += acc[ai][bj][m][0]; h1 += acc[ai][bj][m][1];
;                     const int col0 = c0 + bj * HALF;
;                     u32x4 w; w.x = cvt_pk_bf16(h0[0], h0[1]); w.y = cvt_pk_bf16(h0[2], h0[3]); w.z = cvt_pk_bf16(h1[0], h1[1]); w.w = cvt_pk_bf16(h1[2], h1[3]);
;                     if (valid) *(u32x4*)(HB + (size_t)r * 2048 + col0) = w;
.LBB0_226:
	s_or_b64 exec, exec, s[8:9]
	v_lshlrev_b32_e32 v84, 16, v164
	s_waitcnt lgkmcnt(0)
	v_and_b32_e32 v85, 0xffff0000, v164
	v_lshlrev_b32_e32 v92, 16, v166
	v_and_b32_e32 v93, 0xffff0000, v166
	v_lshlrev_b32_e32 v94, 16, v167
	v_and_b32_e32 v95, 0xffff0000, v167
	v_pk_add_f32 v[76:77], v[76:77], v[84:85]
	v_pk_add_f32 v[84:85], v[74:75], v[94:95]
	v_pk_add_f32 v[74:75], v[72:73], v[92:93]
	v_cvt_pk_bf16_f32 v72, v76, v77
	v_lshl_add_u64 v[76:77], s[34:35], 0, v[212:213]
	v_cmp_gt_i32_e32 vcc, s84, v214
	v_lshlrev_b32_e32 v86, 16, v165
	v_and_b32_e32 v87, 0xffff0000, v165
	v_lshl_add_u64 v[76:77], v[200:201], 1, v[76:77]
	v_pk_add_f32 v[78:79], v[78:79], v[86:87]
	s_nop 0
	v_cvt_pk_bf16_f32 v73, v78, v79
	v_cvt_pk_bf16_f32 v74, v74, v75
	v_cvt_pk_bf16_f32 v75, v84, v85
	s_and_saveexec_b64 s[8:9], vcc
	s_cbranch_execz .LBB0_228
	global_store_dwordx4 v[76:77], v[72:75], off sc1
.LBB0_228:
	s_or_b64 exec, exec, s[8:9]
	v_lshlrev_b32_e32 v78, 16, v160
	v_and_b32_e32 v79, 0xffff0000, v160
	v_lshlrev_b32_e32 v86, 16, v162
	v_and_b32_e32 v87, 0xffff0000, v162
	v_lshlrev_b32_e32 v92, 16, v163
	v_and_b32_e32 v93, 0xffff0000, v163
	v_lshlrev_b32_e32 v84, 16, v161
	v_and_b32_e32 v85, 0xffff0000, v161
	v_pk_add_f32 v[68:69], v[68:69], v[78:79]
	v_pk_add_f32 v[78:79], v[66:67], v[92:93]
	v_pk_add_f32 v[66:67], v[64:65], v[86:87]
	v_pk_add_f32 v[70:71], v[70:71], v[84:85]
	v_cvt_pk_bf16_f32 v64, v68, v69
	s_nop 0
	v_cvt_pk_bf16_f32 v65, v70, v71
	v_cvt_pk_bf16_f32 v66, v66, v67
	v_cvt_pk_bf16_f32 v67, v78, v79
	s_and_saveexec_b64 s[8:9], vcc
	s_cbranch_execz .LBB0_230
	global_store_dwordx4 v[76:77], v[64:67], off offset:256 sc1

; __device__ __forceinline__ unsigned cvt_pk_bf16(float lo, float hi) { unsigned r; asm volatile("v_cvt_pk_bf16_f32 %0, %1, %2" : "=v"(r) : "v"(lo), "v"(hi)); return r; }
;     __device__ __forceinline__ void operator()(const f32x4 (&acc)[2][2][4][2], const Unit& u, int wr, int wc, int fr, int fq) const {
;     ...
;         for (int ai = 0; ai < 2; ++ai)
; #pragma unroll
;             for (int m = 0; m < 4; ++m) {
;                 const int r = r0 + ai * HALF + m * 16;
;                 const bool valid = r < NREAL + NMETA;
;                 float ssum = 0.f;
; #pragma unroll
;                 for (int bj = 0; bj < 2; ++bj) {
;                     const u32x4 hv = hold[ai][m][bj];
;                     f32x4 h0 = {__uint_as_float(hv.x << 16), __uint_as_float(hv.x & 0xffff0000u), __uint_as_float(hv.y << 16), __uint_as_float(hv.y & 0xffff0000u)};
;                     f32x4 h1 = {__uint_as_float(hv.z << 16), __uint_as_float(hv.z & 0xffff0000u), __uint_as_float(hv.w << 16), __uint_as_float(hv.w & 0xffff0000u)};
;                     h0 += acc[ai][bj][m][0]; h1 += acc[ai][bj][m][1];
;                     const int col0 = c0 + bj * HALF;
;                     u32x4 w; w.x = cvt_pk_bf16(h0[0], h0[1]); w.y = cvt_pk_bf16(h0[2], h0[3]); w.z = cvt_pk_bf16(h1[0], h1[1]); w.w = cvt_pk_bf16(h1[2], h1[3]);
;                     if (valid) *(u32x4*)(HB + (size_t)r * 2048 + col0) = w;
.LBB0_232:
	s_or_b64 exec, exec, s[8:9]
	v_lshlrev_b32_e32 v64, 16, v156
	s_waitcnt lgkmcnt(0)
	v_and_b32_e32 v65, 0xffff0000, v156
	v_lshlrev_b32_e32 v68, 16, v158
	v_and_b32_e32 v69, 0xffff0000, v158
	v_lshlrev_b32_e32 v70, 16, v159
	v_and_b32_e32 v71, 0xffff0000, v159
	v_pk_add_f32 v[60:61], v[60:61], v[64:65]
	s_movk_i32 s3, 0x6010
	v_pk_add_f32 v[64:65], v[58:59], v[70:71]
	v_pk_add_f32 v[58:59], v[56:57], v[68:69]
	v_cvt_pk_bf16_f32 v56, v60, v61
	v_lshl_add_u64 v[60:61], s[34:35], 0, v[210:211]
	v_cmp_gt_i32_e32 vcc, s3, v202
	v_lshlrev_b32_e32 v66, 16, v157
	v_and_b32_e32 v67, 0xffff0000, v157
	v_lshl_add_u64 v[60:61], v[200:201], 1, v[60:61]
	v_pk_add_f32 v[62:63], v[62:63], v[66:67]
	s_nop 0
	v_cvt_pk_bf16_f32 v57, v62, v63
	v_cvt_pk_bf16_f32 v58, v58, v59
	v_cvt_pk_bf16_f32 v59, v64, v65
	s_and_saveexec_b64 s[8:9], vcc
	s_cbranch_execz .LBB0_234
	global_store_dwordx4 v[60:61], v[56:59], off sc1
.LBB0_234:
	s_or_b64 exec, exec, s[8:9]
	v_lshlrev_b32_e32 v62, 16, v152
	v_and_b32_e32 v63, 0xffff0000, v152
	v_lshlrev_b32_e32 v66, 16, v154
	v_and_b32_e32 v67, 0xffff0000, v154
	v_lshlrev_b32_e32 v68, 16, v155
	v_and_b32_e32 v69, 0xffff0000, v155
	v_lshlrev_b32_e32 v64, 16, v153
	v_and_b32_e32 v65, 0xffff0000, v153
	v_pk_add_f32 v[52:53], v[52:53], v[62:63]
	v_pk_add_f32 v[62:63], v[50:51], v[68:69]
	v_pk_add_f32 v[50:51], v[48:49], v[66:67]
	v_pk_add_f32 v[54:55], v[54:55], v[64:65]
	v_cvt_pk_bf16_f32 v48, v52, v53
	s_nop 0
	v_cvt_pk_bf16_f32 v49, v54, v55
	v_cvt_pk_bf16_f32 v50, v50, v51
	v_cvt_pk_bf16_f32 v51, v62, v63
	s_and_saveexec_b64 s[8:9], vcc
	s_cbranch_execz .LBB0_236
	global_store_dwordx4 v[60:61], v[48:51], off offset:256 sc1

; __device__ __forceinline__ unsigned cvt_pk_bf16(float lo, float hi) { unsigned r; asm volatile("v_cvt_pk_bf16_f32 %0, %1, %2" : "=v"(r) : "v"(lo), "v"(hi)); return r; }
;     __device__ __forceinline__ void operator()(const f32x4 (&acc)[2][2][4][2], const Unit& u, int wr, int wc, int fr, int fq) const {
;     ...
;         for (int ai = 0; ai < 2; ++ai)
; #pragma unroll
;             for (int m = 0; m < 4; ++m) {
;                 const int r = r0 + ai * HALF + m * 16;
;                 const bool valid = r < NREAL + NMETA;
;                 float ssum = 0.f;
; #pragma unroll
;                 for (int bj = 0; bj < 2; ++bj) {
;                     const u32x4 hv = hold[ai][m][bj];
;                     f32x4 h0 = {__uint_as_float(hv.x << 16), __uint_as_float(hv.x & 0xffff0000u), __uint_as_float(hv.y << 16), __uint_as_float(hv.y & 0xffff0000u)};
;                     f32x4 h1 = {__uint_as_float(hv.z << 16), __uint_as_float(hv.z & 0xffff0000u), __uint_as_float(hv.w << 16), __uint_as_float(hv.w & 0xffff0000u)};
;                     h0 += acc[ai][bj][m][0]; h1 += acc[ai][bj][m][1];
;                     const int col0 = c0 + bj * HALF;
;                     u32x4 w; w.x = cvt_pk_bf16(h0[0], h0[1]); w.y = cvt_pk_bf16(h0[2], h0[3]); w.z = cvt_pk_bf16(h1[0], h1[1]); w.w = cvt_pk_bf16(h1[2], h1[3]);
;                     if (valid) *(u32x4*)(HB + (size_t)r * 2048 + col0) = w;
.LBB0_238:
	s_or_b64 exec, exec, s[8:9]
	v_lshlrev_b32_e32 v48, 16, v132
	s_waitcnt lgkmcnt(0)
	v_and_b32_e32 v49, 0xffff0000, v132
	v_lshlrev_b32_e32 v52, 16, v134
	v_and_b32_e32 v53, 0xffff0000, v134
	v_lshlrev_b32_e32 v54, 16, v135
	v_and_b32_e32 v55, 0xffff0000, v135
	v_pk_add_f32 v[44:45], v[44:45], v[48:49]
	v_pk_add_f32 v[48:49], v[42:43], v[54:55]
	v_pk_add_f32 v[42:43], v[40:41], v[52:53]
	v_cvt_pk_bf16_f32 v40, v44, v45
	v_lshl_add_u64 v[44:45], s[34:35], 0, v[208:209]
	v_cmp_gt_i32_e32 vcc, s43, v202
	v_lshlrev_b32_e32 v50, 16, v133
	v_and_b32_e32 v51, 0xffff0000, v133
	v_lshl_add_u64 v[44:45], v[200:201], 1, v[44:45]
	v_pk_add_f32 v[46:47], v[46:47], v[50:51]
	s_nop 0
	v_cvt_pk_bf16_f32 v41, v46, v47
	v_cvt_pk_bf16_f32 v42, v42, v43
	v_cvt_pk_bf16_f32 v43, v48, v49
	s_and_saveexec_b64 s[8:9], vcc
	s_cbranch_execz .LBB0_240
	global_store_dwordx4 v[44:45], v[40:43], off sc1
.LBB0_240:
	s_or_b64 exec, exec, s[8:9]
	v_lshlrev_b32_e32 v46, 16, v128
	v_and_b32_e32 v47, 0xffff0000, v128
	v_lshlrev_b32_e32 v50, 16, v130
	v_and_b32_e32 v51, 0xffff0000, v130
	v_lshlrev_b32_e32 v52, 16, v131
	v_and_b32_e32 v53, 0xffff0000, v131
	v_lshlrev_b32_e32 v48, 16, v129
	v_and_b32_e32 v49, 0xffff0000, v129
	v_pk_add_f32 v[36:37], v[36:37], v[46:47]
	v_pk_add_f32 v[46:47], v[34:35], v[52:53]
	v_pk_add_f32 v[34:35], v[32:33], v[50:51]
	v_pk_add_f32 v[38:39], v[38:39], v[48:49]
	v_cvt_pk_bf16_f32 v32, v36, v37
	s_nop 0
	v_cvt_pk_bf16_f32 v33, v38, v39
	v_cvt_pk_bf16_f32 v34, v34, v35
	v_cvt_pk_bf16_f32 v35, v46, v47
	s_and_saveexec_b64 s[8:9], vcc
	s_cbranch_execz .LBB0_242
	global_store_dwordx4 v[44:45], v[32:35], off offset:256 sc1

; __device__ __forceinline__ unsigned cvt_pk_bf16(float lo, float hi) { unsigned r; asm volatile("v_cvt_pk_bf16_f32 %0, %1, %2" : "=v"(r) : "v"(lo), "v"(hi)); return r; }
;     __device__ __forceinline__ void operator()(const f32x4 (&acc)[2][2][4][2], const Unit& u, int wr, int wc, int fr, int fq) const {
;     ...
;         for (int ai = 0; ai < 2; ++ai)
; #pragma unroll
;             for (int m = 0; m < 4; ++m) {
;                 const int r = r0 + ai * HALF + m * 16;
;                 const bool valid = r < NREAL + NMETA;
;                 float ssum = 0.f;
; #pragma unroll
;                 for (int bj = 0; bj < 2; ++bj) {
;                     const u32x4 hv = hold[ai][m][bj];
;                     f32x4 h0 = {__uint_as_float(hv.x << 16), __uint_as_float(hv.x & 0xffff0000u), __uint_as_float(hv.y << 16), __uint_as_float(hv.y & 0xffff0000u)};
;                     f32x4 h1 = {__uint_as_float(hv.z << 16), __uint_as_float(hv.z & 0xffff0000u), __uint_as_float(hv.w << 16), __uint_as_float(hv.w & 0xffff0000u)};
;                     h0 += acc[ai][bj][m][0]; h1 += acc[ai][bj][m][1];
;                     const int col0 = c0 + bj * HALF;
;                     u32x4 w; w.x = cvt_pk_bf16(h0[0], h0[1]); w.y = cvt_pk_bf16(h0[2], h0[3]); w.z = cvt_pk_bf16(h1[0], h1[1]); w.w = cvt_pk_bf16(h1[2], h1[3]);
;                     if (valid) *(u32x4*)(HB + (size_t)r * 2048 + col0) = w;
.LBB0_244:
	s_or_b64 exec, exec, s[8:9]
	v_lshlrev_b32_e32 v32, 16, v108
	s_waitcnt lgkmcnt(0)
	v_and_b32_e32 v33, 0xffff0000, v108
	v_lshlrev_b32_e32 v36, 16, v110
	v_and_b32_e32 v37, 0xffff0000, v110
	v_lshlrev_b32_e32 v38, 16, v111
	v_and_b32_e32 v39, 0xffff0000, v111
	v_pk_add_f32 v[28:29], v[28:29], v[32:33]
	s_movk_i32 s3, 0x5ff0
	v_pk_add_f32 v[32:33], v[26:27], v[38:39]
	v_pk_add_f32 v[26:27], v[24:25], v[36:37]
	v_cvt_pk_bf16_f32 v24, v28, v29
	v_lshl_add_u64 v[28:29], s[34:35], 0, v[206:207]
	v_cmp_gt_i32_e32 vcc, s3, v202
	v_lshlrev_b32_e32 v34, 16, v109
	v_and_b32_e32 v35, 0xffff0000, v109
	v_lshl_add_u64 v[28:29], v[200:201], 1, v[28:29]
	v_pk_add_f32 v[30:31], v[30:31], v[34:35]
	s_nop 0
	v_cvt_pk_bf16_f32 v25, v30, v31
	v_cvt_pk_bf16_f32 v26, v26, v27
	v_cvt_pk_bf16_f32 v27, v32, v33
	s_and_saveexec_b64 s[8:9], vcc
	s_cbranch_execz .LBB0_246
	global_store_dwordx4 v[28:29], v[24:27], off sc1
.LBB0_246:
	s_or_b64 exec, exec, s[8:9]
	v_lshlrev_b32_e32 v30, 16, v104
	v_and_b32_e32 v31, 0xffff0000, v104
	v_lshlrev_b32_e32 v34, 16, v106
	v_and_b32_e32 v35, 0xffff0000, v106
	v_lshlrev_b32_e32 v36, 16, v107
	v_and_b32_e32 v37, 0xffff0000, v107
	v_lshlrev_b32_e32 v32, 16, v105
	v_and_b32_e32 v33, 0xffff0000, v105
	v_pk_add_f32 v[20:21], v[20:21], v[30:31]
	v_pk_add_f32 v[30:31], v[18:19], v[36:37]
	v_pk_add_f32 v[18:19], v[16:17], v[34:35]
	v_pk_add_f32 v[22:23], v[22:23], v[32:33]
	v_cvt_pk_bf16_f32 v16, v20, v21
	s_nop 0
	v_cvt_pk_bf16_f32 v17, v22, v23
	v_cvt_pk_bf16_f32 v18, v18, v19
	v_cvt_pk_bf16_f32 v19, v30, v31
	s_and_saveexec_b64 s[8:9], vcc
	s_cbranch_execz .LBB0_248
	global_store_dwordx4 v[28:29], v[16:19], off offset:256 sc1

; __device__ __forceinline__ unsigned cvt_pk_bf16(float lo, float hi) { unsigned r; asm volatile("v_cvt_pk_bf16_f32 %0, %1, %2" : "=v"(r) : "v"(lo), "v"(hi)); return r; }
;     __device__ __forceinline__ void operator()(const f32x4 (&acc)[2][2][4][2], const Unit& u, int wr, int wc, int fr, int fq) const {
;     ...
;         for (int ai = 0; ai < 2; ++ai)
; #pragma unroll
;             for (int m = 0; m < 4; ++m) {
;                 const int r = r0 + ai * HALF + m * 16;
;                 const bool valid = r < NREAL + NMETA;
;                 float ssum = 0.f;
; #pragma unroll
;                 for (int bj = 0; bj < 2; ++bj) {
;                     const u32x4 hv = hold[ai][m][bj];
;                     f32x4 h0 = {__uint_as_float(hv.x << 16), __uint_as_float(hv.x & 0xffff0000u), __uint_as_float(hv.y << 16), __uint_as_float(hv.y & 0xffff0000u)};
;                     f32x4 h1 = {__uint_as_float(hv.z << 16), __uint_as_float(hv.z & 0xffff0000u), __uint_as_float(hv.w << 16), __uint_as_float(hv.w & 0xffff0000u)};
;                     h0 += acc[ai][bj][m][0]; h1 += acc[ai][bj][m][1];
;                     const int col0 = c0 + bj * HALF;
;                     u32x4 w; w.x = cvt_pk_bf16(h0[0], h0[1]); w.y = cvt_pk_bf16(h0[2], h0[3]); w.z = cvt_pk_bf16(h1[0], h1[1]); w.w = cvt_pk_bf16(h1[2], h1[3]);
;                     if (valid) *(u32x4*)(HB + (size_t)r * 2048 + col0) = w;
.LBB0_250:
	s_or_b64 exec, exec, s[8:9]
	v_lshlrev_b32_e32 v16, 16, v88
	s_waitcnt lgkmcnt(0)
	v_and_b32_e32 v17, 0xffff0000, v88
	v_lshlrev_b32_e32 v20, 16, v90
	v_and_b32_e32 v21, 0xffff0000, v90
	v_lshlrev_b32_e32 v22, 16, v91
	v_and_b32_e32 v23, 0xffff0000, v91
	v_pk_add_f32 v[12:13], v[12:13], v[16:17]
	s_movk_i32 s3, 0x5fe0
	v_pk_add_f32 v[16:17], v[10:11], v[22:23]
	v_pk_add_f32 v[10:11], v[8:9], v[20:21]
	v_cvt_pk_bf16_f32 v8, v12, v13
	v_lshl_add_u64 v[12:13], s[34:35], 0, v[204:205]
	v_cmp_gt_i32_e32 vcc, s3, v202
	v_lshlrev_b32_e32 v18, 16, v89
	v_and_b32_e32 v19, 0xffff0000, v89
	v_lshl_add_u64 v[12:13], v[200:201], 1, v[12:13]
	v_pk_add_f32 v[14:15], v[14:15], v[18:19]
	s_nop 0
	v_cvt_pk_bf16_f32 v9, v14, v15
	v_cvt_pk_bf16_f32 v10, v10, v11
	v_cvt_pk_bf16_f32 v11, v16, v17
	s_and_saveexec_b64 s[8:9], vcc
	s_cbranch_execz .LBB0_252
	global_store_dwordx4 v[12:13], v[8:11], off sc1
.LBB0_252:
	s_or_b64 exec, exec, s[8:9]
	v_lshlrev_b32_e32 v14, 16, v80
	v_and_b32_e32 v15, 0xffff0000, v80
	v_lshlrev_b32_e32 v18, 16, v82
	v_and_b32_e32 v19, 0xffff0000, v82
	v_lshlrev_b32_e32 v20, 16, v83
	v_and_b32_e32 v21, 0xffff0000, v83
	v_lshlrev_b32_e32 v16, 16, v81
	v_and_b32_e32 v17, 0xffff0000, v81
	v_pk_add_f32 v[4:5], v[4:5], v[14:15]
	v_pk_add_f32 v[14:15], v[2:3], v[20:21]
	v_pk_add_f32 v[2:3], v[0:1], v[18:19]
	v_pk_add_f32 v[6:7], v[6:7], v[16:17]
	v_cvt_pk_bf16_f32 v0, v4, v5
	s_nop 0
	v_cvt_pk_bf16_f32 v1, v6, v7
	v_cvt_pk_bf16_f32 v2, v2, v3
	v_cvt_pk_bf16_f32 v3, v14, v15
	s_and_saveexec_b64 s[8:9], vcc
	s_cbranch_execz .LBB0_254
	global_store_dwordx4 v[12:13], v[0:3], off offset:256 sc1

; __device__ __forceinline__ unsigned cvt_pk_bf16(float lo, float hi) { unsigned r; asm volatile("v_cvt_pk_bf16_f32 %0, %1, %2" : "=v"(r) : "v"(lo), "v"(hi)); return r; }
; __device__ __forceinline__ float silu_f(float x) { return x * __builtin_amdgcn_rcpf(1.f + __expf(-x)); }
;     __device__ __forceinline__ void operator()(const f32x4 (&acc)[2][2][4][2], const Unit& u, int wr, int wc, int fr, int fq) const {
;     ...
; #pragma unroll
;             for (int ai = 0; ai < 2; ++ai)
; #pragma unroll
;                 for (int m = 0; m < 4; ++m) {
;                     const int r = r0 + ai * HALF + m * 16;
;                     const float rs = __builtin_amdgcn_rsqf(rstd[ai][m] * (1.f / 2048.f) + 1e-6f);
; #pragma unroll
;                     for (int bj = 0; bj < 2; ++bj) {
;                         f32x4 v0 = acc[ai][bj][m][0] * rs, v1 = acc[ai][bj][m][1] * rs;
;                         if (pn >= 12) {
; #pragma unroll
;                             for (int j = 0; j < 4; ++j) { v0[j] = silu_f(v0[j]); v1[j] = silu_f(v1[j]); }
;                         }
;                         bf16_t* dst = (pn < 12) ? KV + (size_t)r * 1024 + 512 + (2 * (pn - 10) + bj) * 128 : GZ + (size_t)r * 2048 + (pn - 12) * 256 + bj * 128;
;                         dst += 32 * wc + 8 * fq;
;                         u32x4 w; w.x = cvt_pk_bf16(v0[0], v0[1]); w.y = cvt_pk_bf16(v0[2], v0[3]); w.z = cvt_pk_bf16(v1[0], v1[1]); w.w = cvt_pk_bf16(v1[2], v1[3]);
;                         *(u32x4*)dst = w;
;                     }
;                 }
.LBB0_356:
	v_lshlrev_b32_e32 v188, 1, v164
	v_lshl_add_u64 v[140:141], v[140:141], 0, v[188:189]
	v_cvt_pk_bf16_f32 v134, v134, v135
	v_mov_b32_e32 v197, v196
	v_cvt_pk_bf16_f32 v135, v130, v131
	v_cvt_pk_bf16_f32 v136, v136, v137
	v_cvt_pk_bf16_f32 v137, v132, v133
	global_store_dwordx4 v[140:141], v[134:137], off sc1
	v_mov_b32_e32 v130, v196
	v_mov_b32_e32 v131, v196
	v_cndmask_b32_e64 v134, 0, 1, s[10:11]
	v_pk_mul_f32 v[132:133], v[118:119], v[130:131]
	v_pk_mul_f32 v[136:137], v[116:117], v[196:197]
	v_pk_mul_f32 v[130:131], v[114:115], v[130:131]
	v_cmp_ne_u32_e64 s[8:9], 1, v134
	s_andn2_b64 vcc, exec, s[10:11]
	v_pk_mul_f32 v[134:135], v[112:113], v[196:197]
	s_cbranch_vccnz .LBB0_358
	v_mul_f32_e32 v141, 0xbfb8aa3b, v134
	v_exp_f32_e32 v141, v141
	v_mul_f32_e32 v140, 0xbfb8aa3b, v136
	v_exp_f32_e32 v140, v140
	v_mul_f32_e32 v145, 0xbfb8aa3b, v130
	v_add_f32_e32 v141, 1.0, v141
	v_rcp_f32_e32 v142, v141
	v_mul_f32_e32 v141, 0xbfb8aa3b, v137
	v_exp_f32_e32 v141, v141
	v_add_f32_e32 v140, 1.0, v140
	v_exp_f32_e32 v145, v145
	v_rcp_f32_e32 v140, v140
	v_add_f32_e32 v141, 1.0, v141
	v_rcp_f32_e32 v141, v141
	v_add_f32_e32 v145, 1.0, v145
	v_mul_f32_e32 v143, 0xbfb8aa3b, v135
	v_mul_f32_e32 v144, 0xbfb8aa3b, v132
	v_rcp_f32_e32 v146, v145
	v_mul_f32_e32 v145, 0xbfb8aa3b, v133
	v_pk_mul_f32 v[136:137], v[136:137], v[140:141]
	v_mul_f32_e32 v140, 0xbfb8aa3b, v131
	v_exp_f32_e32 v143, v143
	v_exp_f32_e32 v144, v144
	v_exp_f32_e32 v145, v145
	v_exp_f32_e32 v140, v140
	v_add_f32_e32 v143, 1.0, v143
	v_add_f32_e32 v144, 1.0, v144
	v_add_f32_e32 v145, 1.0, v145
	v_add_f32_e32 v140, 1.0, v140
	v_rcp_f32_e32 v143, v143
	v_rcp_f32_e32 v144, v144
	v_rcp_f32_e32 v145, v145
	v_rcp_f32_e32 v147, v140
	v_pk_mul_f32 v[134:135], v[134:135], v[142:143]
	v_pk_mul_f32 v[132:133], v[132:133], v[144:145]
	v_pk_mul_f32 v[130:131], v[130:131], v[146:147]
.LBB0_358:
	s_lshl_b32 s62, s3, 1
	s_mov_b32 s63, s99
	v_lshl_add_u64 v[138:139], v[138:139], 0, s[62:63]
	v_lshl_add_u64 v[138:139], v[138:139], 0, s[46:47]
	v_lshl_add_u64 v[128:129], v[128:129], 0, s[96:97]
	v_cndmask_b32_e64 v129, v129, v139, s[6:7]
	v_cndmask_b32_e64 v128, v128, v138, s[6:7]
	v_lshl_add_u64 v[140:141], v[128:129], 0, v[188:189]
	v_fmamk_f32 v128, v211, 0x3a000000, v227
	v_rsq_f32_e32 v128, v128
	v_cvt_pk_bf16_f32 v136, v136, v137
	v_cvt_pk_bf16_f32 v137, v132, v133
	v_cvt_pk_bf16_f32 v138, v134, v135
	v_cvt_pk_bf16_f32 v139, v130, v131
	global_store_dwordx4 v[140:141], v[136:139], off sc1
	v_pk_mul_f32 v[132:133], v[110:111], v[128:129] op_sel_hi:[1,0]
	v_pk_mul_f32 v[134:135], v[106:107], v[128:129] op_sel_hi:[1,0]
	v_pk_mul_f32 v[136:137], v[108:109], v[128:129] op_sel_hi:[1,0]
	s_and_b64 vcc, exec, s[8:9]
	v_pk_mul_f32 v[140:141], v[104:105], v[128:129] op_sel_hi:[1,0]
	s_cbranch_vccnz .LBB0_360
	v_mul_f32_e32 v129, 0xbfb8aa3b, v136
	v_exp_f32_e32 v129, v129
	s_nop 0
	v_add_f32_e32 v129, 1.0, v129
	v_rcp_f32_e32 v130, v129
	v_mul_f32_e32 v129, 0xbfb8aa3b, v140
	v_exp_f32_e32 v129, v129
	s_nop 0
	v_add_f32_e32 v129, 1.0, v129
	v_rcp_f32_e32 v138, v129
	v_mul_f32_e32 v129, 0xbfb8aa3b, v137
	v_exp_f32_e32 v129, v129
	s_nop 0
	v_add_f32_e32 v129, 1.0, v129
	v_rcp_f32_e32 v131, v129
	v_mul_f32_e32 v129, 0xbfb8aa3b, v141
	v_exp_f32_e32 v129, v129
	v_pk_mul_f32 v[136:137], v[136:137], v[130:131]
	v_add_f32_e32 v129, 1.0, v129
	v_rcp_f32_e32 v139, v129
	v_mul_f32_e32 v129, 0xbfb8aa3b, v132
	v_exp_f32_e32 v129, v129
	v_pk_mul_f32 v[140:141], v[140:141], v[138:139]
	v_add_f32_e32 v129, 1.0, v129
	v_rcp_f32_e32 v142, v129
	v_mul_f32_e32 v129, 0xbfb8aa3b, v134
	v_exp_f32_e32 v129, v129
	s_nop 0
	v_add_f32_e32 v129, 1.0, v129
	v_rcp_f32_e32 v144, v129
	v_mul_f32_e32 v129, 0xbfb8aa3b, v133
	v_exp_f32_e32 v129, v129
	s_nop 0
	v_add_f32_e32 v129, 1.0, v129
	v_rcp_f32_e32 v143, v129
	v_mul_f32_e32 v129, 0xbfb8aa3b, v135
	v_exp_f32_e32 v129, v129
	v_pk_mul_f32 v[132:133], v[132:133], v[142:143]
	v_add_f32_e32 v129, 1.0, v129
	v_rcp_f32_e32 v145, v129
	s_nop 0
	v_pk_mul_f32 v[134:135], v[134:135], v[144:145]

; __device__ __forceinline__ unsigned cvt_pk_bf16(float lo, float hi) { unsigned r; asm volatile("v_cvt_pk_bf16_f32 %0, %1, %2" : "=v"(r) : "v"(lo), "v"(hi)); return r; }
; __device__ __forceinline__ float silu_f(float x) { return x * __builtin_amdgcn_rcpf(1.f + __expf(-x)); }
;     __device__ __forceinline__ void operator()(const f32x4 (&acc)[2][2][4][2], const Unit& u, int wr, int wc, int fr, int fq) const {
;     ...
; #pragma unroll
;             for (int ai = 0; ai < 2; ++ai)
; #pragma unroll
;                 for (int m = 0; m < 4; ++m) {
;                     const int r = r0 + ai * HALF + m * 16;
;                     const float rs = __builtin_amdgcn_rsqf(rstd[ai][m] * (1.f / 2048.f) + 1e-6f);
; #pragma unroll
;                     for (int bj = 0; bj < 2; ++bj) {
;                         f32x4 v0 = acc[ai][bj][m][0] * rs, v1 = acc[ai][bj][m][1] * rs;
;                         if (pn >= 12) {
; #pragma unroll
;                             for (int j = 0; j < 4; ++j) { v0[j] = silu_f(v0[j]); v1[j] = silu_f(v1[j]); }
;                         }
;                         bf16_t* dst = (pn < 12) ? KV + (size_t)r * 1024 + 512 + (2 * (pn - 10) + bj) * 128 : GZ + (size_t)r * 2048 + (pn - 12) * 256 + bj * 128;
;                         dst += 32 * wc + 8 * fq;
;                         u32x4 w; w.x = cvt_pk_bf16(v0[0], v0[1]); w.y = cvt_pk_bf16(v0[2], v0[3]); w.z = cvt_pk_bf16(v1[0], v1[1]); w.w = cvt_pk_bf16(v1[2], v1[3]);
;                         *(u32x4*)dst = w;
;                     }
;                 }
.LBB0_364:
	v_mov_b32_e32 v129, v128
	v_lshl_add_u64 v[146:147], v[142:143], 0, v[188:189]
	v_cvt_pk_bf16_f32 v142, v136, v137
	v_cvt_pk_bf16_f32 v143, v132, v133
	v_mov_b32_e32 v132, v128
	v_mov_b32_e32 v133, v128
	v_cvt_pk_bf16_f32 v144, v140, v141
	v_cvt_pk_bf16_f32 v145, v134, v135
	v_pk_mul_f32 v[134:135], v[102:103], v[132:133]
	v_pk_mul_f32 v[140:141], v[100:101], v[128:129]
	v_pk_mul_f32 v[132:133], v[98:99], v[132:133]
	s_and_b64 vcc, exec, s[8:9]
	v_pk_mul_f32 v[136:137], v[96:97], v[128:129]
	global_store_dwordx4 v[146:147], v[142:145], off sc1
	s_cbranch_vccnz .LBB0_366
	v_mul_f32_e32 v129, 0xbfb8aa3b, v136
	v_exp_f32_e32 v129, v129
	v_mul_f32_e32 v128, 0xbfb8aa3b, v140
	v_exp_f32_e32 v128, v128
	v_mul_f32_e32 v145, 0xbfb8aa3b, v132
	v_add_f32_e32 v129, 1.0, v129
	v_rcp_f32_e32 v142, v129
	v_mul_f32_e32 v129, 0xbfb8aa3b, v141
	v_exp_f32_e32 v129, v129
	v_add_f32_e32 v128, 1.0, v128
	v_exp_f32_e32 v145, v145
	v_rcp_f32_e32 v128, v128
	v_add_f32_e32 v129, 1.0, v129
	v_rcp_f32_e32 v129, v129
	v_add_f32_e32 v145, 1.0, v145
	v_mul_f32_e32 v143, 0xbfb8aa3b, v137
	v_mul_f32_e32 v144, 0xbfb8aa3b, v134
	v_rcp_f32_e32 v146, v145
	v_mul_f32_e32 v145, 0xbfb8aa3b, v135
	v_pk_mul_f32 v[140:141], v[140:141], v[128:129]
	v_mul_f32_e32 v128, 0xbfb8aa3b, v133
	v_exp_f32_e32 v143, v143
	v_exp_f32_e32 v144, v144
	v_exp_f32_e32 v145, v145
	v_exp_f32_e32 v128, v128
	v_add_f32_e32 v143, 1.0, v143
	v_add_f32_e32 v144, 1.0, v144
	v_add_f32_e32 v145, 1.0, v145
	v_add_f32_e32 v128, 1.0, v128
	v_rcp_f32_e32 v143, v143
	v_rcp_f32_e32 v144, v144
	v_rcp_f32_e32 v145, v145
	v_rcp_f32_e32 v147, v128
	v_pk_mul_f32 v[136:137], v[136:137], v[142:143]
	v_pk_mul_f32 v[134:135], v[134:135], v[144:145]
	v_pk_mul_f32 v[132:133], v[132:133], v[146:147]
.LBB0_366:
	s_mov_b32 s63, s99
	v_lshl_add_u64 v[128:129], v[138:139], 0, s[62:63]
	v_lshl_add_u64 v[128:129], v[128:129], 0, s[46:47]
	v_lshl_add_u64 v[130:131], v[130:131], 0, s[96:97]
	v_cndmask_b32_e64 v129, v131, v129, s[6:7]
	v_cndmask_b32_e64 v128, v130, v128, s[6:7]
	v_lshl_add_u64 v[130:131], v[128:129], 0, v[188:189]
	v_fmamk_f32 v128, v210, 0x3a000000, v227
	v_rsq_f32_e32 v128, v128
	v_cvt_pk_bf16_f32 v138, v140, v141
	v_cvt_pk_bf16_f32 v139, v134, v135
	v_cvt_pk_bf16_f32 v140, v136, v137
	v_cvt_pk_bf16_f32 v141, v132, v133
	global_store_dwordx4 v[130:131], v[138:141], off sc1
	v_pk_mul_f32 v[132:133], v[94:95], v[128:129] op_sel_hi:[1,0]
	v_pk_mul_f32 v[134:135], v[90:91], v[128:129] op_sel_hi:[1,0]
	v_pk_mul_f32 v[138:139], v[92:93], v[128:129] op_sel_hi:[1,0]
	s_and_b64 vcc, exec, s[8:9]
	v_pk_mul_f32 v[140:141], v[88:89], v[128:129] op_sel_hi:[1,0]
	s_cbranch_vccnz .LBB0_368
	v_mul_f32_e32 v129, 0xbfb8aa3b, v138
	v_exp_f32_e32 v129, v129
	s_nop 0
	v_add_f32_e32 v129, 1.0, v129
	v_rcp_f32_e32 v130, v129
	v_mul_f32_e32 v129, 0xbfb8aa3b, v140
	v_exp_f32_e32 v129, v129
	s_nop 0
	v_add_f32_e32 v129, 1.0, v129
	v_rcp_f32_e32 v136, v129
	v_mul_f32_e32 v129, 0xbfb8aa3b, v139
	v_exp_f32_e32 v129, v129
	s_nop 0
	v_add_f32_e32 v129, 1.0, v129
	v_rcp_f32_e32 v131, v129
	v_mul_f32_e32 v129, 0xbfb8aa3b, v141
	v_exp_f32_e32 v129, v129
	v_pk_mul_f32 v[138:139], v[138:139], v[130:131]
	v_add_f32_e32 v129, 1.0, v129
	v_rcp_f32_e32 v137, v129
	v_mul_f32_e32 v129, 0xbfb8aa3b, v132
	v_exp_f32_e32 v129, v129
	v_pk_mul_f32 v[140:141], v[140:141], v[136:137]
	v_add_f32_e32 v129, 1.0, v129
	v_rcp_f32_e32 v142, v129
	v_mul_f32_e32 v129, 0xbfb8aa3b, v134
	v_exp_f32_e32 v129, v129
	s_nop 0
	v_add_f32_e32 v129, 1.0, v129
	v_rcp_f32_e32 v144, v129
	v_mul_f32_e32 v129, 0xbfb8aa3b, v133
	v_exp_f32_e32 v129, v129
	s_nop 0
	v_add_f32_e32 v129, 1.0, v129
	v_rcp_f32_e32 v143, v129
	v_mul_f32_e32 v129, 0xbfb8aa3b, v135
	v_exp_f32_e32 v129, v129
	v_pk_mul_f32 v[132:133], v[132:133], v[142:143]
	v_add_f32_e32 v129, 1.0, v129
	v_rcp_f32_e32 v145, v129
	s_nop 0
	v_pk_mul_f32 v[134:135], v[134:135], v[144:145]

; __device__ __forceinline__ unsigned cvt_pk_bf16(float lo, float hi) { unsigned r; asm volatile("v_cvt_pk_bf16_f32 %0, %1, %2" : "=v"(r) : "v"(lo), "v"(hi)); return r; }
; __device__ __forceinline__ float silu_f(float x) { return x * __builtin_amdgcn_rcpf(1.f + __expf(-x)); }
;     __device__ __forceinline__ void operator()(const f32x4 (&acc)[2][2][4][2], const Unit& u, int wr, int wc, int fr, int fq) const {
;     ...
; #pragma unroll
;             for (int ai = 0; ai < 2; ++ai)
; #pragma unroll
;                 for (int m = 0; m < 4; ++m) {
;                     const int r = r0 + ai * HALF + m * 16;
;                     const float rs = __builtin_amdgcn_rsqf(rstd[ai][m] * (1.f / 2048.f) + 1e-6f);
; #pragma unroll
;                     for (int bj = 0; bj < 2; ++bj) {
;                         f32x4 v0 = acc[ai][bj][m][0] * rs, v1 = acc[ai][bj][m][1] * rs;
;                         if (pn >= 12) {
; #pragma unroll
;                             for (int j = 0; j < 4; ++j) { v0[j] = silu_f(v0[j]); v1[j] = silu_f(v1[j]); }
;                         }
;                         bf16_t* dst = (pn < 12) ? KV + (size_t)r * 1024 + 512 + (2 * (pn - 10) + bj) * 128 : GZ + (size_t)r * 2048 + (pn - 12) * 256 + bj * 128;
;                         dst += 32 * wc + 8 * fq;
;                         u32x4 w; w.x = cvt_pk_bf16(v0[0], v0[1]); w.y = cvt_pk_bf16(v0[2], v0[3]); w.z = cvt_pk_bf16(v1[0], v1[1]); w.w = cvt_pk_bf16(v1[2], v1[3]);
;                         *(u32x4*)dst = w;
;                     }
;                 }
.LBB0_372:
	v_mov_b32_e32 v129, v128
	v_lshl_add_u64 v[142:143], v[142:143], 0, v[188:189]
	v_cvt_pk_bf16_f32 v138, v138, v139
	v_cvt_pk_bf16_f32 v139, v132, v133
	v_cvt_pk_bf16_f32 v140, v140, v141
	v_cvt_pk_bf16_f32 v141, v134, v135
	v_mov_b32_e32 v132, v128
	v_mov_b32_e32 v133, v128
	global_store_dwordx4 v[142:143], v[138:141], off sc1
	v_pk_mul_f32 v[134:135], v[86:87], v[132:133]
	v_pk_mul_f32 v[132:133], v[82:83], v[132:133]
	v_pk_mul_f32 v[140:141], v[84:85], v[128:129]
	s_and_b64 vcc, exec, s[8:9]
	v_pk_mul_f32 v[138:139], v[80:81], v[128:129]
	s_cbranch_vccnz .LBB0_374
	v_mul_f32_e32 v129, 0xbfb8aa3b, v138
	v_exp_f32_e32 v129, v129
	v_mul_f32_e32 v128, 0xbfb8aa3b, v140
	v_exp_f32_e32 v128, v128
	v_mul_f32_e32 v145, 0xbfb8aa3b, v132
	v_add_f32_e32 v129, 1.0, v129
	v_rcp_f32_e32 v142, v129
	v_mul_f32_e32 v129, 0xbfb8aa3b, v141
	v_exp_f32_e32 v129, v129
	v_add_f32_e32 v128, 1.0, v128
	v_exp_f32_e32 v145, v145
	v_rcp_f32_e32 v128, v128
	v_add_f32_e32 v129, 1.0, v129
	v_rcp_f32_e32 v129, v129
	v_add_f32_e32 v145, 1.0, v145
	v_mul_f32_e32 v143, 0xbfb8aa3b, v139
	v_mul_f32_e32 v144, 0xbfb8aa3b, v134
	v_rcp_f32_e32 v146, v145
	v_mul_f32_e32 v145, 0xbfb8aa3b, v135
	v_pk_mul_f32 v[140:141], v[140:141], v[128:129]
	v_mul_f32_e32 v128, 0xbfb8aa3b, v133
	v_exp_f32_e32 v143, v143
	v_exp_f32_e32 v144, v144
	v_exp_f32_e32 v145, v145
	v_exp_f32_e32 v128, v128
	v_add_f32_e32 v143, 1.0, v143
	v_add_f32_e32 v144, 1.0, v144
	v_add_f32_e32 v145, 1.0, v145
	v_add_f32_e32 v128, 1.0, v128
	v_rcp_f32_e32 v143, v143
	v_rcp_f32_e32 v144, v144
	v_rcp_f32_e32 v145, v145
	v_rcp_f32_e32 v147, v128
	v_pk_mul_f32 v[138:139], v[138:139], v[142:143]
	v_pk_mul_f32 v[134:135], v[134:135], v[144:145]
	v_pk_mul_f32 v[132:133], v[132:133], v[146:147]
.LBB0_374:
	s_mov_b32 s63, s99
	v_lshl_add_u64 v[128:129], v[136:137], 0, s[62:63]
	v_lshl_add_u64 v[128:129], v[128:129], 0, s[46:47]
	v_lshl_add_u64 v[130:131], v[130:131], 0, s[96:97]
	v_cndmask_b32_e64 v129, v131, v129, s[6:7]
	v_cndmask_b32_e64 v128, v130, v128, s[6:7]
	v_lshl_add_u64 v[130:131], v[128:129], 0, v[188:189]
	v_fmamk_f32 v128, v209, 0x3a000000, v227
	v_rsq_f32_e32 v128, v128
	v_cvt_pk_bf16_f32 v136, v140, v141
	v_cvt_pk_bf16_f32 v137, v134, v135
	v_cvt_pk_bf16_f32 v138, v138, v139
	v_cvt_pk_bf16_f32 v139, v132, v133
	global_store_dwordx4 v[130:131], v[136:139], off sc1
	v_pk_mul_f32 v[132:133], v[78:79], v[128:129] op_sel_hi:[1,0]
	v_pk_mul_f32 v[134:135], v[74:75], v[128:129] op_sel_hi:[1,0]
	v_pk_mul_f32 v[138:139], v[76:77], v[128:129] op_sel_hi:[1,0]
	s_and_b64 vcc, exec, s[8:9]
	v_pk_mul_f32 v[140:141], v[72:73], v[128:129] op_sel_hi:[1,0]
	s_cbranch_vccnz .LBB0_376
	v_mul_f32_e32 v129, 0xbfb8aa3b, v138
	v_exp_f32_e32 v129, v129
	s_nop 0
	v_add_f32_e32 v129, 1.0, v129
	v_rcp_f32_e32 v130, v129
	v_mul_f32_e32 v129, 0xbfb8aa3b, v140
	v_exp_f32_e32 v129, v129
	s_nop 0
	v_add_f32_e32 v129, 1.0, v129
	v_rcp_f32_e32 v136, v129
	v_mul_f32_e32 v129, 0xbfb8aa3b, v139
	v_exp_f32_e32 v129, v129
	s_nop 0
	v_add_f32_e32 v129, 1.0, v129
	v_rcp_f32_e32 v131, v129
	v_mul_f32_e32 v129, 0xbfb8aa3b, v141
	v_exp_f32_e32 v129, v129
	v_pk_mul_f32 v[138:139], v[138:139], v[130:131]
	v_add_f32_e32 v129, 1.0, v129
	v_rcp_f32_e32 v137, v129
	v_mul_f32_e32 v129, 0xbfb8aa3b, v132
	v_exp_f32_e32 v129, v129
	v_pk_mul_f32 v[140:141], v[140:141], v[136:137]
	v_add_f32_e32 v129, 1.0, v129
	v_rcp_f32_e32 v142, v129
	v_mul_f32_e32 v129, 0xbfb8aa3b, v134
	v_exp_f32_e32 v129, v129
	s_nop 0
	v_add_f32_e32 v129, 1.0, v129
	v_rcp_f32_e32 v144, v129
	v_mul_f32_e32 v129, 0xbfb8aa3b, v133
	v_exp_f32_e32 v129, v129
	s_nop 0
	v_add_f32_e32 v129, 1.0, v129
	v_rcp_f32_e32 v143, v129
	v_mul_f32_e32 v129, 0xbfb8aa3b, v135
	v_exp_f32_e32 v129, v129
	v_pk_mul_f32 v[132:133], v[132:133], v[142:143]
	v_add_f32_e32 v129, 1.0, v129
	v_rcp_f32_e32 v145, v129
	s_nop 0
	v_pk_mul_f32 v[134:135], v[134:135], v[144:145]

; __device__ __forceinline__ unsigned cvt_pk_bf16(float lo, float hi) { unsigned r; asm volatile("v_cvt_pk_bf16_f32 %0, %1, %2" : "=v"(r) : "v"(lo), "v"(hi)); return r; }
; __device__ __forceinline__ float silu_f(float x) { return x * __builtin_amdgcn_rcpf(1.f + __expf(-x)); }
;     __device__ __forceinline__ void operator()(const f32x4 (&acc)[2][2][4][2], const Unit& u, int wr, int wc, int fr, int fq) const {
;     ...
; #pragma unroll
;             for (int ai = 0; ai < 2; ++ai)
; #pragma unroll
;                 for (int m = 0; m < 4; ++m) {
;                     const int r = r0 + ai * HALF + m * 16;
;                     const float rs = __builtin_amdgcn_rsqf(rstd[ai][m] * (1.f / 2048.f) + 1e-6f);
; #pragma unroll
;                     for (int bj = 0; bj < 2; ++bj) {
;                         f32x4 v0 = acc[ai][bj][m][0] * rs, v1 = acc[ai][bj][m][1] * rs;
;                         if (pn >= 12) {
; #pragma unroll
;                             for (int j = 0; j < 4; ++j) { v0[j] = silu_f(v0[j]); v1[j] = silu_f(v1[j]); }
;                         }
;                         bf16_t* dst = (pn < 12) ? KV + (size_t)r * 1024 + 512 + (2 * (pn - 10) + bj) * 128 : GZ + (size_t)r * 2048 + (pn - 12) * 256 + bj * 128;
;                         dst += 32 * wc + 8 * fq;
;                         u32x4 w; w.x = cvt_pk_bf16(v0[0], v0[1]); w.y = cvt_pk_bf16(v0[2], v0[3]); w.z = cvt_pk_bf16(v1[0], v1[1]); w.w = cvt_pk_bf16(v1[2], v1[3]);
;                         *(u32x4*)dst = w;
;                     }
;                 }
.LBB0_380:
	v_mov_b32_e32 v129, v128
	v_lshl_add_u64 v[142:143], v[142:143], 0, v[188:189]
	v_cvt_pk_bf16_f32 v138, v138, v139
	v_cvt_pk_bf16_f32 v139, v132, v133
	v_cvt_pk_bf16_f32 v140, v140, v141
	v_cvt_pk_bf16_f32 v141, v134, v135
	v_mov_b32_e32 v132, v128
	v_mov_b32_e32 v133, v128
	global_store_dwordx4 v[142:143], v[138:141], off sc1
	v_pk_mul_f32 v[134:135], v[70:71], v[132:133]
	v_pk_mul_f32 v[132:133], v[66:67], v[132:133]
	v_pk_mul_f32 v[140:141], v[68:69], v[128:129]
	s_and_b64 vcc, exec, s[8:9]
	v_pk_mul_f32 v[138:139], v[64:65], v[128:129]
	s_cbranch_vccnz .LBB0_382
	v_mul_f32_e32 v129, 0xbfb8aa3b, v138
	v_exp_f32_e32 v129, v129
	v_mul_f32_e32 v128, 0xbfb8aa3b, v140
	v_exp_f32_e32 v128, v128
	v_mul_f32_e32 v145, 0xbfb8aa3b, v132
	v_add_f32_e32 v129, 1.0, v129
	v_rcp_f32_e32 v142, v129
	v_mul_f32_e32 v129, 0xbfb8aa3b, v141
	v_exp_f32_e32 v129, v129
	v_add_f32_e32 v128, 1.0, v128
	v_exp_f32_e32 v145, v145
	v_rcp_f32_e32 v128, v128
	v_add_f32_e32 v129, 1.0, v129
	v_rcp_f32_e32 v129, v129
	v_add_f32_e32 v145, 1.0, v145
	v_mul_f32_e32 v143, 0xbfb8aa3b, v139
	v_mul_f32_e32 v144, 0xbfb8aa3b, v134
	v_rcp_f32_e32 v146, v145
	v_mul_f32_e32 v145, 0xbfb8aa3b, v135
	v_pk_mul_f32 v[140:141], v[140:141], v[128:129]
	v_mul_f32_e32 v128, 0xbfb8aa3b, v133
	v_exp_f32_e32 v143, v143
	v_exp_f32_e32 v144, v144
	v_exp_f32_e32 v145, v145
	v_exp_f32_e32 v128, v128
	v_add_f32_e32 v143, 1.0, v143
	v_add_f32_e32 v144, 1.0, v144
	v_add_f32_e32 v145, 1.0, v145
	v_add_f32_e32 v128, 1.0, v128
	v_rcp_f32_e32 v143, v143
	v_rcp_f32_e32 v144, v144
	v_rcp_f32_e32 v145, v145
	v_rcp_f32_e32 v147, v128
	v_pk_mul_f32 v[138:139], v[138:139], v[142:143]
	v_pk_mul_f32 v[134:135], v[134:135], v[144:145]
	v_pk_mul_f32 v[132:133], v[132:133], v[146:147]
.LBB0_382:
	s_mov_b32 s63, s99
	v_lshl_add_u64 v[128:129], v[136:137], 0, s[62:63]
	v_lshl_add_u64 v[128:129], v[128:129], 0, s[46:47]
	v_lshl_add_u64 v[130:131], v[130:131], 0, s[96:97]
	v_cndmask_b32_e64 v129, v131, v129, s[6:7]
	v_cndmask_b32_e64 v128, v130, v128, s[6:7]
	v_lshl_add_u64 v[130:131], v[128:129], 0, v[188:189]
	v_fmamk_f32 v128, v207, 0x3a000000, v227
	v_rsq_f32_e32 v128, v128
	v_cvt_pk_bf16_f32 v136, v140, v141
	v_cvt_pk_bf16_f32 v137, v134, v135
	v_cvt_pk_bf16_f32 v138, v138, v139
	v_cvt_pk_bf16_f32 v139, v132, v133
	global_store_dwordx4 v[130:131], v[136:139], off sc1
	v_pk_mul_f32 v[132:133], v[62:63], v[128:129] op_sel_hi:[1,0]
	v_pk_mul_f32 v[134:135], v[58:59], v[128:129] op_sel_hi:[1,0]
	v_pk_mul_f32 v[138:139], v[60:61], v[128:129] op_sel_hi:[1,0]
	s_and_b64 vcc, exec, s[8:9]
	v_pk_mul_f32 v[140:141], v[56:57], v[128:129] op_sel_hi:[1,0]
	s_cbranch_vccnz .LBB0_384
	v_mul_f32_e32 v129, 0xbfb8aa3b, v138
	v_exp_f32_e32 v129, v129
	s_nop 0
	v_add_f32_e32 v129, 1.0, v129
	v_rcp_f32_e32 v130, v129
	v_mul_f32_e32 v129, 0xbfb8aa3b, v140
	v_exp_f32_e32 v129, v129
	s_nop 0
	v_add_f32_e32 v129, 1.0, v129
	v_rcp_f32_e32 v136, v129
	v_mul_f32_e32 v129, 0xbfb8aa3b, v139
	v_exp_f32_e32 v129, v129
	s_nop 0
	v_add_f32_e32 v129, 1.0, v129
	v_rcp_f32_e32 v131, v129
	v_mul_f32_e32 v129, 0xbfb8aa3b, v141
	v_exp_f32_e32 v129, v129
	v_pk_mul_f32 v[138:139], v[138:139], v[130:131]
	v_add_f32_e32 v129, 1.0, v129
	v_rcp_f32_e32 v137, v129
	v_mul_f32_e32 v129, 0xbfb8aa3b, v132
	v_exp_f32_e32 v129, v129
	v_pk_mul_f32 v[140:141], v[140:141], v[136:137]
	v_add_f32_e32 v129, 1.0, v129
	v_rcp_f32_e32 v142, v129
	v_mul_f32_e32 v129, 0xbfb8aa3b, v134
	v_exp_f32_e32 v129, v129
	s_nop 0
	v_add_f32_e32 v129, 1.0, v129
	v_rcp_f32_e32 v144, v129
	v_mul_f32_e32 v129, 0xbfb8aa3b, v133
	v_exp_f32_e32 v129, v129
	s_nop 0
	v_add_f32_e32 v129, 1.0, v129
	v_rcp_f32_e32 v143, v129
	v_mul_f32_e32 v129, 0xbfb8aa3b, v135
	v_exp_f32_e32 v129, v129
	v_pk_mul_f32 v[132:133], v[132:133], v[142:143]
	v_add_f32_e32 v129, 1.0, v129
	v_rcp_f32_e32 v145, v129
	s_nop 0
	v_pk_mul_f32 v[134:135], v[134:135], v[144:145]

; __device__ __forceinline__ unsigned cvt_pk_bf16(float lo, float hi) { unsigned r; asm volatile("v_cvt_pk_bf16_f32 %0, %1, %2" : "=v"(r) : "v"(lo), "v"(hi)); return r; }
; __device__ __forceinline__ float silu_f(float x) { return x * __builtin_amdgcn_rcpf(1.f + __expf(-x)); }
;     __device__ __forceinline__ void operator()(const f32x4 (&acc)[2][2][4][2], const Unit& u, int wr, int wc, int fr, int fq) const {
;     ...
; #pragma unroll
;             for (int ai = 0; ai < 2; ++ai)
; #pragma unroll
;                 for (int m = 0; m < 4; ++m) {
;                     const int r = r0 + ai * HALF + m * 16;
;                     const float rs = __builtin_amdgcn_rsqf(rstd[ai][m] * (1.f / 2048.f) + 1e-6f);
; #pragma unroll
;                     for (int bj = 0; bj < 2; ++bj) {
;                         f32x4 v0 = acc[ai][bj][m][0] * rs, v1 = acc[ai][bj][m][1] * rs;
;                         if (pn >= 12) {
; #pragma unroll
;                             for (int j = 0; j < 4; ++j) { v0[j] = silu_f(v0[j]); v1[j] = silu_f(v1[j]); }
;                         }
;                         bf16_t* dst = (pn < 12) ? KV + (size_t)r * 1024 + 512 + (2 * (pn - 10) + bj) * 128 : GZ + (size_t)r * 2048 + (pn - 12) * 256 + bj * 128;
;                         dst += 32 * wc + 8 * fq;
;                         u32x4 w; w.x = cvt_pk_bf16(v0[0], v0[1]); w.y = cvt_pk_bf16(v0[2], v0[3]); w.z = cvt_pk_bf16(v1[0], v1[1]); w.w = cvt_pk_bf16(v1[2], v1[3]);
;                         *(u32x4*)dst = w;
;                     }
;                 }
.LBB0_388:
	v_mov_b32_e32 v129, v128
	v_lshl_add_u64 v[142:143], v[142:143], 0, v[188:189]
	v_cvt_pk_bf16_f32 v138, v138, v139
	v_cvt_pk_bf16_f32 v139, v132, v133
	v_cvt_pk_bf16_f32 v140, v140, v141
	v_cvt_pk_bf16_f32 v141, v134, v135
	v_mov_b32_e32 v132, v128
	v_mov_b32_e32 v133, v128
	global_store_dwordx4 v[142:143], v[138:141], off sc1
	v_pk_mul_f32 v[134:135], v[54:55], v[132:133]
	v_pk_mul_f32 v[132:133], v[50:51], v[132:133]
	v_pk_mul_f32 v[140:141], v[52:53], v[128:129]
	s_and_b64 vcc, exec, s[8:9]
	v_pk_mul_f32 v[138:139], v[48:49], v[128:129]
	s_cbranch_vccnz .LBB0_390
	v_mul_f32_e32 v129, 0xbfb8aa3b, v138
	v_exp_f32_e32 v129, v129
	v_mul_f32_e32 v128, 0xbfb8aa3b, v140
	v_exp_f32_e32 v128, v128
	v_mul_f32_e32 v145, 0xbfb8aa3b, v132
	v_add_f32_e32 v129, 1.0, v129
	v_rcp_f32_e32 v142, v129
	v_mul_f32_e32 v129, 0xbfb8aa3b, v141
	v_exp_f32_e32 v129, v129
	v_add_f32_e32 v128, 1.0, v128
	v_exp_f32_e32 v145, v145
	v_rcp_f32_e32 v128, v128
	v_add_f32_e32 v129, 1.0, v129
	v_rcp_f32_e32 v129, v129
	v_add_f32_e32 v145, 1.0, v145
	v_mul_f32_e32 v143, 0xbfb8aa3b, v139
	v_mul_f32_e32 v144, 0xbfb8aa3b, v134
	v_rcp_f32_e32 v146, v145
	v_mul_f32_e32 v145, 0xbfb8aa3b, v135
	v_pk_mul_f32 v[140:141], v[140:141], v[128:129]
	v_mul_f32_e32 v128, 0xbfb8aa3b, v133
	v_exp_f32_e32 v143, v143
	v_exp_f32_e32 v144, v144
	v_exp_f32_e32 v145, v145
	v_exp_f32_e32 v128, v128
	v_add_f32_e32 v143, 1.0, v143
	v_add_f32_e32 v144, 1.0, v144
	v_add_f32_e32 v145, 1.0, v145
	v_add_f32_e32 v128, 1.0, v128
	v_rcp_f32_e32 v143, v143
	v_rcp_f32_e32 v144, v144
	v_rcp_f32_e32 v145, v145
	v_rcp_f32_e32 v147, v128
	v_pk_mul_f32 v[138:139], v[138:139], v[142:143]
	v_pk_mul_f32 v[134:135], v[134:135], v[144:145]
	v_pk_mul_f32 v[132:133], v[132:133], v[146:147]
.LBB0_390:
	s_mov_b32 s63, s99
	v_lshl_add_u64 v[128:129], v[136:137], 0, s[62:63]
	v_lshl_add_u64 v[128:129], v[128:129], 0, s[46:47]
	v_lshl_add_u64 v[130:131], v[130:131], 0, s[96:97]
	v_cndmask_b32_e64 v129, v131, v129, s[6:7]
	v_cndmask_b32_e64 v128, v130, v128, s[6:7]
	v_lshl_add_u64 v[130:131], v[128:129], 0, v[188:189]
	v_fmamk_f32 v128, v206, 0x3a000000, v227
	v_rsq_f32_e32 v128, v128
	v_cvt_pk_bf16_f32 v136, v140, v141
	v_cvt_pk_bf16_f32 v137, v134, v135
	v_cvt_pk_bf16_f32 v138, v138, v139
	v_cvt_pk_bf16_f32 v139, v132, v133
	global_store_dwordx4 v[130:131], v[136:139], off sc1
	v_pk_mul_f32 v[132:133], v[46:47], v[128:129] op_sel_hi:[1,0]
	v_pk_mul_f32 v[134:135], v[42:43], v[128:129] op_sel_hi:[1,0]
	v_pk_mul_f32 v[138:139], v[44:45], v[128:129] op_sel_hi:[1,0]
	s_and_b64 vcc, exec, s[8:9]
	v_pk_mul_f32 v[140:141], v[40:41], v[128:129] op_sel_hi:[1,0]
	s_cbranch_vccnz .LBB0_392
	v_mul_f32_e32 v129, 0xbfb8aa3b, v138
	v_exp_f32_e32 v129, v129
	s_nop 0
	v_add_f32_e32 v129, 1.0, v129
	v_rcp_f32_e32 v130, v129
	v_mul_f32_e32 v129, 0xbfb8aa3b, v140
	v_exp_f32_e32 v129, v129
	s_nop 0
	v_add_f32_e32 v129, 1.0, v129
	v_rcp_f32_e32 v136, v129
	v_mul_f32_e32 v129, 0xbfb8aa3b, v139
	v_exp_f32_e32 v129, v129
	s_nop 0
	v_add_f32_e32 v129, 1.0, v129
	v_rcp_f32_e32 v131, v129
	v_mul_f32_e32 v129, 0xbfb8aa3b, v141
	v_exp_f32_e32 v129, v129
	v_pk_mul_f32 v[138:139], v[138:139], v[130:131]
	v_add_f32_e32 v129, 1.0, v129
	v_rcp_f32_e32 v137, v129
	v_mul_f32_e32 v129, 0xbfb8aa3b, v132
	v_exp_f32_e32 v129, v129
	v_pk_mul_f32 v[140:141], v[140:141], v[136:137]
	v_add_f32_e32 v129, 1.0, v129
	v_rcp_f32_e32 v142, v129
	v_mul_f32_e32 v129, 0xbfb8aa3b, v134
	v_exp_f32_e32 v129, v129
	s_nop 0
	v_add_f32_e32 v129, 1.0, v129
	v_rcp_f32_e32 v144, v129
	v_mul_f32_e32 v129, 0xbfb8aa3b, v133
	v_exp_f32_e32 v129, v129
	s_nop 0
	v_add_f32_e32 v129, 1.0, v129
	v_rcp_f32_e32 v143, v129
	v_mul_f32_e32 v129, 0xbfb8aa3b, v135
	v_exp_f32_e32 v129, v129
	v_pk_mul_f32 v[132:133], v[132:133], v[142:143]
	v_add_f32_e32 v129, 1.0, v129
	v_rcp_f32_e32 v145, v129
	s_nop 0
	v_pk_mul_f32 v[134:135], v[134:135], v[144:145]

; __device__ __forceinline__ unsigned cvt_pk_bf16(float lo, float hi) { unsigned r; asm volatile("v_cvt_pk_bf16_f32 %0, %1, %2" : "=v"(r) : "v"(lo), "v"(hi)); return r; }
; __device__ __forceinline__ float silu_f(float x) { return x * __builtin_amdgcn_rcpf(1.f + __expf(-x)); }
;     __device__ __forceinline__ void operator()(const f32x4 (&acc)[2][2][4][2], const Unit& u, int wr, int wc, int fr, int fq) const {
;     ...
; #pragma unroll
;             for (int ai = 0; ai < 2; ++ai)
; #pragma unroll
;                 for (int m = 0; m < 4; ++m) {
;                     const int r = r0 + ai * HALF + m * 16;
;                     const float rs = __builtin_amdgcn_rsqf(rstd[ai][m] * (1.f / 2048.f) + 1e-6f);
; #pragma unroll
;                     for (int bj = 0; bj < 2; ++bj) {
;                         f32x4 v0 = acc[ai][bj][m][0] * rs, v1 = acc[ai][bj][m][1] * rs;
;                         if (pn >= 12) {
; #pragma unroll
;                             for (int j = 0; j < 4; ++j) { v0[j] = silu_f(v0[j]); v1[j] = silu_f(v1[j]); }
;                         }
;                         bf16_t* dst = (pn < 12) ? KV + (size_t)r * 1024 + 512 + (2 * (pn - 10) + bj) * 128 : GZ + (size_t)r * 2048 + (pn - 12) * 256 + bj * 128;
;                         dst += 32 * wc + 8 * fq;
;                         u32x4 w; w.x = cvt_pk_bf16(v0[0], v0[1]); w.y = cvt_pk_bf16(v0[2], v0[3]); w.z = cvt_pk_bf16(v1[0], v1[1]); w.w = cvt_pk_bf16(v1[2], v1[3]);
;                         *(u32x4*)dst = w;
;                     }
;                 }
.LBB0_396:
	v_mov_b32_e32 v129, v128
	v_lshl_add_u64 v[142:143], v[142:143], 0, v[188:189]
	v_cvt_pk_bf16_f32 v138, v138, v139
	v_cvt_pk_bf16_f32 v139, v132, v133
	v_cvt_pk_bf16_f32 v140, v140, v141
	v_cvt_pk_bf16_f32 v141, v134, v135
	v_mov_b32_e32 v132, v128
	v_mov_b32_e32 v133, v128
	global_store_dwordx4 v[142:143], v[138:141], off sc1
	v_pk_mul_f32 v[134:135], v[38:39], v[132:133]
	v_pk_mul_f32 v[132:133], v[34:35], v[132:133]
	v_pk_mul_f32 v[140:141], v[36:37], v[128:129]
	s_and_b64 vcc, exec, s[8:9]
	v_pk_mul_f32 v[138:139], v[32:33], v[128:129]
	s_cbranch_vccnz .LBB0_398
	v_mul_f32_e32 v129, 0xbfb8aa3b, v138
	v_exp_f32_e32 v129, v129
	v_mul_f32_e32 v128, 0xbfb8aa3b, v140
	v_exp_f32_e32 v128, v128
	v_mul_f32_e32 v145, 0xbfb8aa3b, v132
	v_add_f32_e32 v129, 1.0, v129
	v_rcp_f32_e32 v142, v129
	v_mul_f32_e32 v129, 0xbfb8aa3b, v141
	v_exp_f32_e32 v129, v129
	v_add_f32_e32 v128, 1.0, v128
	v_exp_f32_e32 v145, v145
	v_rcp_f32_e32 v128, v128
	v_add_f32_e32 v129, 1.0, v129
	v_rcp_f32_e32 v129, v129
	v_add_f32_e32 v145, 1.0, v145
	v_mul_f32_e32 v143, 0xbfb8aa3b, v139
	v_mul_f32_e32 v144, 0xbfb8aa3b, v134
	v_rcp_f32_e32 v146, v145
	v_mul_f32_e32 v145, 0xbfb8aa3b, v135
	v_pk_mul_f32 v[140:141], v[140:141], v[128:129]
	v_mul_f32_e32 v128, 0xbfb8aa3b, v133
	v_exp_f32_e32 v143, v143
	v_exp_f32_e32 v144, v144
	v_exp_f32_e32 v145, v145
	v_exp_f32_e32 v128, v128
	v_add_f32_e32 v143, 1.0, v143
	v_add_f32_e32 v144, 1.0, v144
	v_add_f32_e32 v145, 1.0, v145
	v_add_f32_e32 v128, 1.0, v128
	v_rcp_f32_e32 v143, v143
	v_rcp_f32_e32 v144, v144
	v_rcp_f32_e32 v145, v145
	v_rcp_f32_e32 v147, v128
	v_pk_mul_f32 v[138:139], v[138:139], v[142:143]
	v_pk_mul_f32 v[134:135], v[134:135], v[144:145]
	v_pk_mul_f32 v[132:133], v[132:133], v[146:147]
.LBB0_398:
	s_mov_b32 s63, s99
	v_lshl_add_u64 v[128:129], v[136:137], 0, s[62:63]
	v_lshl_add_u64 v[128:129], v[128:129], 0, s[46:47]
	v_lshl_add_u64 v[130:131], v[130:131], 0, s[96:97]
	v_cndmask_b32_e64 v129, v131, v129, s[6:7]
	v_cndmask_b32_e64 v128, v130, v128, s[6:7]
	v_lshl_add_u64 v[130:131], v[128:129], 0, v[188:189]
	v_fmamk_f32 v128, v205, 0x3a000000, v227
	v_rsq_f32_e32 v128, v128
	v_cvt_pk_bf16_f32 v136, v140, v141
	v_cvt_pk_bf16_f32 v137, v134, v135
	v_cvt_pk_bf16_f32 v138, v138, v139
	v_cvt_pk_bf16_f32 v139, v132, v133
	global_store_dwordx4 v[130:131], v[136:139], off sc1
	v_pk_mul_f32 v[132:133], v[30:31], v[128:129] op_sel_hi:[1,0]
	v_pk_mul_f32 v[134:135], v[26:27], v[128:129] op_sel_hi:[1,0]
	v_pk_mul_f32 v[138:139], v[28:29], v[128:129] op_sel_hi:[1,0]
	s_and_b64 vcc, exec, s[8:9]
	v_pk_mul_f32 v[140:141], v[24:25], v[128:129] op_sel_hi:[1,0]
	s_cbranch_vccnz .LBB0_400
	v_mul_f32_e32 v129, 0xbfb8aa3b, v138
	v_exp_f32_e32 v129, v129
	s_nop 0
	v_add_f32_e32 v129, 1.0, v129
	v_rcp_f32_e32 v130, v129
	v_mul_f32_e32 v129, 0xbfb8aa3b, v140
	v_exp_f32_e32 v129, v129
	s_nop 0
	v_add_f32_e32 v129, 1.0, v129
	v_rcp_f32_e32 v136, v129
	v_mul_f32_e32 v129, 0xbfb8aa3b, v139
	v_exp_f32_e32 v129, v129
	s_nop 0
	v_add_f32_e32 v129, 1.0, v129
	v_rcp_f32_e32 v131, v129
	v_mul_f32_e32 v129, 0xbfb8aa3b, v141
	v_exp_f32_e32 v129, v129
	v_pk_mul_f32 v[138:139], v[138:139], v[130:131]
	v_add_f32_e32 v129, 1.0, v129
	v_rcp_f32_e32 v137, v129
	v_mul_f32_e32 v129, 0xbfb8aa3b, v132
	v_exp_f32_e32 v129, v129
	v_pk_mul_f32 v[140:141], v[140:141], v[136:137]
	v_add_f32_e32 v129, 1.0, v129
	v_rcp_f32_e32 v142, v129
	v_mul_f32_e32 v129, 0xbfb8aa3b, v134
	v_exp_f32_e32 v129, v129
	s_nop 0
	v_add_f32_e32 v129, 1.0, v129
	v_rcp_f32_e32 v144, v129
	v_mul_f32_e32 v129, 0xbfb8aa3b, v133
	v_exp_f32_e32 v129, v129
	s_nop 0
	v_add_f32_e32 v129, 1.0, v129
	v_rcp_f32_e32 v143, v129
	v_mul_f32_e32 v129, 0xbfb8aa3b, v135
	v_exp_f32_e32 v129, v129
	v_pk_mul_f32 v[132:133], v[132:133], v[142:143]
	v_add_f32_e32 v129, 1.0, v129
	v_rcp_f32_e32 v145, v129
	s_nop 0
	v_pk_mul_f32 v[134:135], v[134:135], v[144:145]

; __device__ __forceinline__ unsigned cvt_pk_bf16(float lo, float hi) { unsigned r; asm volatile("v_cvt_pk_bf16_f32 %0, %1, %2" : "=v"(r) : "v"(lo), "v"(hi)); return r; }
; __device__ __forceinline__ float silu_f(float x) { return x * __builtin_amdgcn_rcpf(1.f + __expf(-x)); }
;     __device__ __forceinline__ void operator()(const f32x4 (&acc)[2][2][4][2], const Unit& u, int wr, int wc, int fr, int fq) const {
;     ...
; #pragma unroll
;             for (int ai = 0; ai < 2; ++ai)
; #pragma unroll
;                 for (int m = 0; m < 4; ++m) {
;                     const int r = r0 + ai * HALF + m * 16;
;                     const float rs = __builtin_amdgcn_rsqf(rstd[ai][m] * (1.f / 2048.f) + 1e-6f);
; #pragma unroll
;                     for (int bj = 0; bj < 2; ++bj) {
;                         f32x4 v0 = acc[ai][bj][m][0] * rs, v1 = acc[ai][bj][m][1] * rs;
;                         if (pn >= 12) {
; #pragma unroll
;                             for (int j = 0; j < 4; ++j) { v0[j] = silu_f(v0[j]); v1[j] = silu_f(v1[j]); }
;                         }
;                         bf16_t* dst = (pn < 12) ? KV + (size_t)r * 1024 + 512 + (2 * (pn - 10) + bj) * 128 : GZ + (size_t)r * 2048 + (pn - 12) * 256 + bj * 128;
;                         dst += 32 * wc + 8 * fq;
;                         u32x4 w; w.x = cvt_pk_bf16(v0[0], v0[1]); w.y = cvt_pk_bf16(v0[2], v0[3]); w.z = cvt_pk_bf16(v1[0], v1[1]); w.w = cvt_pk_bf16(v1[2], v1[3]);
;                         *(u32x4*)dst = w;
;                     }
;                 }
.LBB0_404:
	v_mov_b32_e32 v129, v128
	v_lshl_add_u64 v[142:143], v[142:143], 0, v[188:189]
	v_cvt_pk_bf16_f32 v138, v138, v139
	v_cvt_pk_bf16_f32 v139, v132, v133
	v_cvt_pk_bf16_f32 v140, v140, v141
	v_cvt_pk_bf16_f32 v141, v134, v135
	v_mov_b32_e32 v132, v128
	v_mov_b32_e32 v133, v128
	global_store_dwordx4 v[142:143], v[138:141], off sc1
	v_pk_mul_f32 v[134:135], v[22:23], v[132:133]
	v_pk_mul_f32 v[132:133], v[18:19], v[132:133]
	v_pk_mul_f32 v[140:141], v[20:21], v[128:129]
	s_and_b64 vcc, exec, s[8:9]
	v_pk_mul_f32 v[138:139], v[16:17], v[128:129]
	s_cbranch_vccnz .LBB0_406
	v_mul_f32_e32 v129, 0xbfb8aa3b, v138
	v_exp_f32_e32 v129, v129
	v_mul_f32_e32 v128, 0xbfb8aa3b, v140
	v_exp_f32_e32 v128, v128
	v_mul_f32_e32 v145, 0xbfb8aa3b, v132
	v_add_f32_e32 v129, 1.0, v129
	v_rcp_f32_e32 v142, v129
	v_mul_f32_e32 v129, 0xbfb8aa3b, v141
	v_exp_f32_e32 v129, v129
	v_add_f32_e32 v128, 1.0, v128
	v_exp_f32_e32 v145, v145
	v_rcp_f32_e32 v128, v128
	v_add_f32_e32 v129, 1.0, v129
	v_rcp_f32_e32 v129, v129
	v_add_f32_e32 v145, 1.0, v145
	v_mul_f32_e32 v143, 0xbfb8aa3b, v139
	v_mul_f32_e32 v144, 0xbfb8aa3b, v134
	v_rcp_f32_e32 v146, v145
	v_mul_f32_e32 v145, 0xbfb8aa3b, v135
	v_pk_mul_f32 v[140:141], v[140:141], v[128:129]
	v_mul_f32_e32 v128, 0xbfb8aa3b, v133
	v_exp_f32_e32 v143, v143
	v_exp_f32_e32 v144, v144
	v_exp_f32_e32 v145, v145
	v_exp_f32_e32 v128, v128
	v_add_f32_e32 v143, 1.0, v143
	v_add_f32_e32 v144, 1.0, v144
	v_add_f32_e32 v145, 1.0, v145
	v_add_f32_e32 v128, 1.0, v128
	v_rcp_f32_e32 v143, v143
	v_rcp_f32_e32 v144, v144
	v_rcp_f32_e32 v145, v145
	v_rcp_f32_e32 v147, v128
	v_pk_mul_f32 v[138:139], v[138:139], v[142:143]
	v_pk_mul_f32 v[134:135], v[134:135], v[144:145]
	v_pk_mul_f32 v[132:133], v[132:133], v[146:147]
.LBB0_406:
	s_mov_b32 s63, s99
	v_lshl_add_u64 v[128:129], v[136:137], 0, s[62:63]
	v_lshl_add_u64 v[128:129], v[128:129], 0, s[46:47]
	v_lshl_add_u64 v[130:131], v[130:131], 0, s[96:97]
	v_cndmask_b32_e64 v129, v131, v129, s[6:7]
	v_cndmask_b32_e64 v128, v130, v128, s[6:7]
	v_lshl_add_u64 v[130:131], v[128:129], 0, v[188:189]
	v_fmamk_f32 v128, v208, 0x3a000000, v227
	v_rsq_f32_e32 v128, v128
	v_cvt_pk_bf16_f32 v136, v140, v141
	v_cvt_pk_bf16_f32 v137, v134, v135
	v_cvt_pk_bf16_f32 v138, v138, v139
	v_cvt_pk_bf16_f32 v139, v132, v133
	global_store_dwordx4 v[130:131], v[136:139], off sc1
	v_pk_mul_f32 v[132:133], v[14:15], v[128:129] op_sel_hi:[1,0]
	v_pk_mul_f32 v[134:135], v[10:11], v[128:129] op_sel_hi:[1,0]
	v_pk_mul_f32 v[138:139], v[12:13], v[128:129] op_sel_hi:[1,0]
	s_and_b64 vcc, exec, s[8:9]
	v_pk_mul_f32 v[140:141], v[8:9], v[128:129] op_sel_hi:[1,0]
	s_cbranch_vccnz .LBB0_408
	v_mul_f32_e32 v129, 0xbfb8aa3b, v138
	v_exp_f32_e32 v129, v129
	s_nop 0
	v_add_f32_e32 v129, 1.0, v129
	v_rcp_f32_e32 v130, v129
	v_mul_f32_e32 v129, 0xbfb8aa3b, v140
	v_exp_f32_e32 v129, v129
	s_nop 0
	v_add_f32_e32 v129, 1.0, v129
	v_rcp_f32_e32 v136, v129
	v_mul_f32_e32 v129, 0xbfb8aa3b, v139
	v_exp_f32_e32 v129, v129
	s_nop 0
	v_add_f32_e32 v129, 1.0, v129
	v_rcp_f32_e32 v131, v129
	v_mul_f32_e32 v129, 0xbfb8aa3b, v141
	v_exp_f32_e32 v129, v129
	v_pk_mul_f32 v[138:139], v[138:139], v[130:131]
	v_add_f32_e32 v129, 1.0, v129
	v_rcp_f32_e32 v137, v129
	v_mul_f32_e32 v129, 0xbfb8aa3b, v132
	v_exp_f32_e32 v129, v129
	v_pk_mul_f32 v[140:141], v[140:141], v[136:137]
	v_add_f32_e32 v129, 1.0, v129
	v_rcp_f32_e32 v142, v129
	v_mul_f32_e32 v129, 0xbfb8aa3b, v134
	v_exp_f32_e32 v129, v129
	s_nop 0
	v_add_f32_e32 v129, 1.0, v129
	v_rcp_f32_e32 v144, v129
	v_mul_f32_e32 v129, 0xbfb8aa3b, v133
	v_exp_f32_e32 v129, v129
	s_nop 0
	v_add_f32_e32 v129, 1.0, v129
	v_rcp_f32_e32 v143, v129
	v_mul_f32_e32 v129, 0xbfb8aa3b, v135
	v_exp_f32_e32 v129, v129
	v_pk_mul_f32 v[132:133], v[132:133], v[142:143]
	v_add_f32_e32 v129, 1.0, v129
	v_rcp_f32_e32 v145, v129
	s_nop 0
	v_pk_mul_f32 v[134:135], v[134:135], v[144:145]

; __device__ __forceinline__ unsigned cvt_pk_bf16(float lo, float hi) { unsigned r; asm volatile("v_cvt_pk_bf16_f32 %0, %1, %2" : "=v"(r) : "v"(lo), "v"(hi)); return r; }
; __device__ __forceinline__ float silu_f(float x) { return x * __builtin_amdgcn_rcpf(1.f + __expf(-x)); }
;     __device__ __forceinline__ void operator()(const f32x4 (&acc)[2][2][4][2], const Unit& u, int wr, int wc, int fr, int fq) const {
;     ...
; #pragma unroll
;             for (int ai = 0; ai < 2; ++ai)
; #pragma unroll
;                 for (int m = 0; m < 4; ++m) {
;                     const int r = r0 + ai * HALF + m * 16;
;                     const float rs = __builtin_amdgcn_rsqf(rstd[ai][m] * (1.f / 2048.f) + 1e-6f);
; #pragma unroll
;                     for (int bj = 0; bj < 2; ++bj) {
;                         f32x4 v0 = acc[ai][bj][m][0] * rs, v1 = acc[ai][bj][m][1] * rs;
;                         if (pn >= 12) {
; #pragma unroll
;                             for (int j = 0; j < 4; ++j) { v0[j] = silu_f(v0[j]); v1[j] = silu_f(v1[j]); }
;                         }
;                         bf16_t* dst = (pn < 12) ? KV + (size_t)r * 1024 + 512 + (2 * (pn - 10) + bj) * 128 : GZ + (size_t)r * 2048 + (pn - 12) * 256 + bj * 128;
;                         dst += 32 * wc + 8 * fq;
;                         u32x4 w; w.x = cvt_pk_bf16(v0[0], v0[1]); w.y = cvt_pk_bf16(v0[2], v0[3]); w.z = cvt_pk_bf16(v1[0], v1[1]); w.w = cvt_pk_bf16(v1[2], v1[3]);
;                         *(u32x4*)dst = w;
;                     }
;                 }
.LBB0_412:
	v_mov_b32_e32 v129, v128
	v_lshl_add_u64 v[142:143], v[142:143], 0, v[188:189]
	v_cvt_pk_bf16_f32 v138, v138, v139
	v_cvt_pk_bf16_f32 v139, v132, v133
	v_cvt_pk_bf16_f32 v140, v140, v141
	v_cvt_pk_bf16_f32 v141, v134, v135
	v_mov_b32_e32 v134, v128
	v_mov_b32_e32 v135, v128
	global_store_dwordx4 v[142:143], v[138:141], off sc1
	v_pk_mul_f32 v[132:133], v[6:7], v[134:135]
	v_pk_mul_f32 v[134:135], v[2:3], v[134:135]
	v_pk_mul_f32 v[138:139], v[4:5], v[128:129]
	s_and_b64 vcc, exec, s[8:9]
	v_pk_mul_f32 v[128:129], v[0:1], v[128:129]
	s_cbranch_vccnz .LBB0_414
	v_mul_f32_e32 v141, 0xbfb8aa3b, v128
	v_exp_f32_e32 v141, v141
	v_mul_f32_e32 v140, 0xbfb8aa3b, v138
	v_exp_f32_e32 v140, v140
	v_mul_f32_e32 v145, 0xbfb8aa3b, v134
	v_add_f32_e32 v141, 1.0, v141
	v_rcp_f32_e32 v142, v141
	v_mul_f32_e32 v141, 0xbfb8aa3b, v139
	v_exp_f32_e32 v141, v141
	v_add_f32_e32 v140, 1.0, v140
	v_exp_f32_e32 v145, v145
	v_rcp_f32_e32 v140, v140
	v_add_f32_e32 v141, 1.0, v141
	v_rcp_f32_e32 v141, v141
	v_add_f32_e32 v145, 1.0, v145
	v_mul_f32_e32 v143, 0xbfb8aa3b, v129
	v_mul_f32_e32 v144, 0xbfb8aa3b, v132
	v_rcp_f32_e32 v146, v145
	v_mul_f32_e32 v145, 0xbfb8aa3b, v133
	v_pk_mul_f32 v[138:139], v[138:139], v[140:141]
	v_mul_f32_e32 v140, 0xbfb8aa3b, v135
	v_exp_f32_e32 v143, v143
	v_exp_f32_e32 v144, v144
	v_exp_f32_e32 v145, v145
	v_exp_f32_e32 v140, v140
	v_add_f32_e32 v143, 1.0, v143
	v_add_f32_e32 v144, 1.0, v144
	v_add_f32_e32 v145, 1.0, v145
	v_add_f32_e32 v140, 1.0, v140
	v_rcp_f32_e32 v143, v143
	v_rcp_f32_e32 v144, v144
	v_rcp_f32_e32 v145, v145
	v_rcp_f32_e32 v147, v140
	v_pk_mul_f32 v[128:129], v[128:129], v[142:143]
	v_pk_mul_f32 v[132:133], v[132:133], v[144:145]
	v_pk_mul_f32 v[134:135], v[134:135], v[146:147]
.LBB0_414:
	s_mov_b32 s63, s99
	v_lshl_add_u64 v[136:137], v[136:137], 0, s[62:63]
	v_lshl_add_u64 v[136:137], v[136:137], 0, s[46:47]
	v_lshl_add_u64 v[130:131], v[130:131], 0, s[96:97]
	v_cndmask_b32_e64 v131, v131, v137, s[6:7]
	v_cndmask_b32_e64 v130, v130, v136, s[6:7]
	v_lshl_add_u64 v[136:137], v[130:131], 0, v[188:189]
	v_cvt_pk_bf16_f32 v130, v138, v139
	v_cvt_pk_bf16_f32 v131, v132, v133
	v_cvt_pk_bf16_f32 v132, v128, v129
	v_cvt_pk_bf16_f32 v133, v134, v135
	global_store_dwordx4 v[136:137], v[130:133], off sc1
	s_branch .LBB0_349

; #define LAS __attribute__((address_space(3)))
; __device__ __forceinline__ void convert_range(LAS unsigned char* lds, const Params& p, int lo1, int n1, int lo2, int n2, int wi, int nw) {
;     ...
; #pragma unroll
;         for (int e = 0; e < 2; ++e) {
;             const int cid = tid + 512 * e, nl = cid >> 4, kc = cid & 15;
;             u32x4 o; o.x = *(const LAS unsigned*)(lds + nl * 260 + kc * 16); o.y = *(const LAS unsigned*)(lds + nl * 260 + kc * 16 + 4);
;             o.z = *(const LAS unsigned*)(lds + nl * 260 + kc * 16 + 8); o.w = *(const LAS unsigned*)(lds + nl * 260 + kc * 16 + 12);
;             *(u32x4*)(dc.dst + (size_t)(dc.n0 + nl) * 2048 + dc.k0 + kc * 8) = o;
;         }
.LBB0_516:
	s_waitcnt lgkmcnt(0)
	s_barrier
	s_lshl_b64 s[8:9], s[98:99], 1
	ds_read2_b32 v[16:17], v30 offset1:1
	ds_read2_b32 v[18:19], v30 offset0:2 offset1:3
	s_add_u32 s0, s0, s8
	v_add_u32_e32 v34, s3, v27
	s_addc_u32 s1, s1, s9
	v_ashrrev_i32_e32 v35, 31, v34
	v_lshl_add_u64 v[32:33], s[0:1], 0, v[188:189]
	v_lshlrev_b64 v[34:35], 12, v[34:35]
	v_lshl_add_u64 v[34:35], v[32:33], 0, v[34:35]
	s_waitcnt lgkmcnt(0)
	global_store_dwordx4 v[34:35], v[16:19], off sc1
	ds_read2_b32 v[16:17], v31 offset1:1
	ds_read2_b32 v[18:19], v31 offset0:2 offset1:3
	v_add_u32_e32 v34, s3, v28
	v_ashrrev_i32_e32 v35, 31, v34
	s_add_i32 s54, s54, s52
	v_lshlrev_b64 v[34:35], 12, v[34:35]
	s_add_i32 s53, s53, s52
	s_add_i32 s0, s2, s54
	v_lshl_add_u64 v[32:33], v[32:33], 0, v[34:35]
	s_cmp_ge_i32 s0, s44
	s_mov_b64 s[0:1], s[6:7]
	s_mov_b32 s3, s57
	s_mov_b32 s98, s12
	s_waitcnt lgkmcnt(0)
	global_store_dwordx4 v[32:33], v[16:19], off sc1
	s_barrier
	s_cbranch_scc1 .LBB0_48
